# scan body: one counted LDS wait per step instead of two
# baseline (speedup 1.0000x reference)
.Lsc_noinit:
	s_waitcnt lgkmcnt(0)
	v_pk_mul_f32 v[22:23], v[6:7], v[52:53]
	v_pk_mul_f32 v[24:25], v[14:15], v[52:53]
	ds_read_b128 v[94:97], v47 offset:256
	v_pk_mul_f32 v[30:31], v[68:69], v[92:93] op_sel_hi:[1,0]
	v_pk_mul_f32 v[38:39], v[68:69], v[92:93] op_sel:[0,1]
	ds_read_b128 v[98:101], v47 offset:272
	v_pk_fma_f32 v[22:23], v[8:9], v[54:55], v[22:23]
	v_pk_fma_f32 v[24:25], v[16:17], v[54:55], v[24:25]
	ds_read_b128 v[110:113], v47 offset:8448
	v_pk_mul_f32 v[32:33], v[70:71], v[92:93] op_sel_hi:[1,0]
	v_pk_mul_f32 v[40:41], v[70:71], v[92:93] op_sel:[0,1]
	ds_read_b128 v[114:117], v47 offset:8464
	v_pk_fma_f32 v[22:23], v[10:11], v[56:57], v[22:23]
	v_pk_fma_f32 v[24:25], v[18:19], v[56:57], v[24:25]
	ds_read_b64 v[134:135], v48 offset:256
	v_pk_mul_f32 v[34:35], v[72:73], v[92:93] op_sel_hi:[1,0]
	v_pk_mul_f32 v[42:43], v[72:73], v[92:93] op_sel:[0,1]
	ds_read_b128 v[126:129], v47 offset:16640
	v_pk_fma_f32 v[22:23], v[12:13], v[58:59], v[22:23]
	v_pk_fma_f32 v[24:25], v[20:21], v[58:59], v[24:25]
	ds_read_b128 v[130:133], v47 offset:16656
	v_pk_mul_f32 v[36:37], v[74:75], v[92:93] op_sel_hi:[1,0]
	v_pk_mul_f32 v[44:45], v[74:75], v[92:93] op_sel:[0,1]
	ds_read_b128 v[102:105], v47 offset:4352
	v_add_f32_e32 v22, v22, v23
	v_add_f32_e32 v24, v24, v25
	ds_read_b128 v[106:109], v47 offset:4368
	v_pk_fma_f32 v[30:31], v[84:85], v[6:7], v[30:31]
	v_pk_fma_f32 v[38:39], v[84:85], v[14:15], v[38:39]
	ds_read_b128 v[118:121], v47 offset:12544
	v_pk_fma_f32 v[32:33], v[86:87], v[8:9], v[32:33]
	v_pk_fma_f32 v[40:41], v[86:87], v[16:17], v[40:41]
	ds_read_b128 v[122:125], v47 offset:12560
	v_add_f32_dpp v22, v22, v22 quad_perm:[1,0,3,2] row_mask:0xf bank_mask:0xf
	v_add_f32_dpp v24, v24, v24 quad_perm:[1,0,3,2] row_mask:0xf bank_mask:0xf
	v_pk_fma_f32 v[34:35], v[88:89], v[10:11], v[34:35]
	v_pk_fma_f32 v[42:43], v[88:89], v[18:19], v[42:43]
	v_add_f32_dpp v22, v22, v22 quad_perm:[2,3,0,1] row_mask:0xf bank_mask:0xf
	v_add_f32_dpp v24, v24, v24 quad_perm:[2,3,0,1] row_mask:0xf bank_mask:0xf
	v_pk_fma_f32 v[36:37], v[90:91], v[12:13], v[36:37]
	v_pk_fma_f32 v[44:45], v[90:91], v[20:21], v[44:45]
	v_add_f32_dpp v22, v22, v22 row_half_mirror row_mask:0xf bank_mask:0xf
	v_add_f32_dpp v24, v24, v24 row_half_mirror row_mask:0xf bank_mask:0xf
	v_pk_fma_f32 v[6:7], v[60:61], v[22:23], v[30:31] op_sel_hi:[1,0,1] neg_lo:[0,1,0] neg_hi:[0,1,0]
	v_pk_fma_f32 v[14:15], v[60:61], v[24:25], v[38:39] op_sel_hi:[1,0,1] neg_lo:[0,1,0] neg_hi:[0,1,0]
	v_pk_fma_f32 v[8:9], v[62:63], v[22:23], v[32:33] op_sel_hi:[1,0,1] neg_lo:[0,1,0] neg_hi:[0,1,0]
	v_pk_fma_f32 v[16:17], v[62:63], v[24:25], v[40:41] op_sel_hi:[1,0,1] neg_lo:[0,1,0] neg_hi:[0,1,0]
	v_pk_mul_f32 v[26:27], v[6:7], v[76:77]
	v_pk_mul_f32 v[28:29], v[14:15], v[76:77]
	v_pk_fma_f32 v[10:11], v[64:65], v[22:23], v[34:35] op_sel_hi:[1,0,1] neg_lo:[0,1,0] neg_hi:[0,1,0]
	v_pk_fma_f32 v[18:19], v[64:65], v[24:25], v[42:43] op_sel_hi:[1,0,1] neg_lo:[0,1,0] neg_hi:[0,1,0]
	v_pk_fma_f32 v[26:27], v[8:9], v[78:79], v[26:27]
	v_pk_fma_f32 v[28:29], v[16:17], v[78:79], v[28:29]
	v_pk_fma_f32 v[12:13], v[66:67], v[22:23], v[36:37] op_sel_hi:[1,0,1] neg_lo:[0,1,0] neg_hi:[0,1,0]
	v_pk_fma_f32 v[20:21], v[66:67], v[24:25], v[44:45] op_sel_hi:[1,0,1] neg_lo:[0,1,0] neg_hi:[0,1,0]
	v_pk_fma_f32 v[26:27], v[10:11], v[80:81], v[26:27]
	v_pk_fma_f32 v[28:29], v[18:19], v[80:81], v[28:29]
	v_pk_fma_f32 v[26:27], v[12:13], v[82:83], v[26:27]
	v_pk_fma_f32 v[28:29], v[20:21], v[82:83], v[28:29]
	s_waitcnt lgkmcnt(0)
	v_pk_mul_f32 v[22:23], v[6:7], v[94:95]
	v_pk_mul_f32 v[24:25], v[14:15], v[94:95]
	ds_read_b128 v[52:55], v47 offset:512
	v_add_f32_e32 v26, v26, v27
	v_add_f32_e32 v28, v28, v29
	ds_read_b128 v[56:59], v47 offset:528
	v_pk_mul_f32 v[30:31], v[110:111], v[134:135] op_sel_hi:[1,0]
	v_pk_mul_f32 v[38:39], v[110:111], v[134:135] op_sel:[0,1]
	ds_read_b128 v[68:71], v47 offset:8704
	v_pk_fma_f32 v[22:23], v[8:9], v[96:97], v[22:23]
	v_pk_fma_f32 v[24:25], v[16:17], v[96:97], v[24:25]
	ds_read_b128 v[72:75], v47 offset:8720
	v_pk_mul_f32 v[32:33], v[112:113], v[134:135] op_sel_hi:[1,0]
	v_pk_mul_f32 v[40:41], v[112:113], v[134:135] op_sel:[0,1]
	ds_read_b64 v[92:93], v48 offset:512
	v_pk_fma_f32 v[22:23], v[10:11], v[98:99], v[22:23]
	v_pk_fma_f32 v[24:25], v[18:19], v[98:99], v[24:25]
	ds_read_b128 v[84:87], v47 offset:16896
	v_pk_mul_f32 v[34:35], v[114:115], v[134:135] op_sel_hi:[1,0]
	v_pk_mul_f32 v[42:43], v[114:115], v[134:135] op_sel:[0,1]
	ds_read_b128 v[88:91], v47 offset:16912
	v_pk_fma_f32 v[22:23], v[12:13], v[100:101], v[22:23]
	v_pk_fma_f32 v[24:25], v[20:21], v[100:101], v[24:25]
	ds_read_b128 v[60:63], v47 offset:4608
	v_pk_mul_f32 v[36:37], v[116:117], v[134:135] op_sel_hi:[1,0]
	v_pk_mul_f32 v[44:45], v[116:117], v[134:135] op_sel:[0,1]
	ds_read_b128 v[64:67], v47 offset:4624
	v_add_f32_e32 v22, v22, v23
	v_add_f32_e32 v24, v24, v25
	ds_read_b128 v[76:79], v47 offset:12800
	v_pk_fma_f32 v[30:31], v[126:127], v[6:7], v[30:31]
	v_pk_fma_f32 v[38:39], v[126:127], v[14:15], v[38:39]
	ds_read_b128 v[80:83], v47 offset:12816
	v_pk_fma_f32 v[32:33], v[128:129], v[8:9], v[32:33]
	v_pk_fma_f32 v[40:41], v[128:129], v[16:17], v[40:41]
	v_add_f32_dpp v22, v22, v22 quad_perm:[1,0,3,2] row_mask:0xf bank_mask:0xf
	v_add_f32_dpp v24, v24, v24 quad_perm:[1,0,3,2] row_mask:0xf bank_mask:0xf
	v_add_f32_dpp v26, v26, v26 quad_perm:[1,0,3,2] row_mask:0xf bank_mask:0xf
	v_add_f32_dpp v28, v28, v28 quad_perm:[1,0,3,2] row_mask:0xf bank_mask:0xf
	v_pk_fma_f32 v[34:35], v[130:131], v[10:11], v[34:35]
	v_pk_fma_f32 v[42:43], v[130:131], v[18:19], v[42:43]
	v_add_f32_dpp v22, v22, v22 quad_perm:[2,3,0,1] row_mask:0xf bank_mask:0xf
	v_add_f32_dpp v24, v24, v24 quad_perm:[2,3,0,1] row_mask:0xf bank_mask:0xf
	v_add_f32_dpp v26, v26, v26 quad_perm:[2,3,0,1] row_mask:0xf bank_mask:0xf
	v_add_f32_dpp v28, v28, v28 quad_perm:[2,3,0,1] row_mask:0xf bank_mask:0xf
	v_pk_fma_f32 v[36:37], v[132:133], v[12:13], v[36:37]
	v_pk_fma_f32 v[44:45], v[132:133], v[20:21], v[44:45]
	v_add_f32_dpp v22, v22, v22 row_half_mirror row_mask:0xf bank_mask:0xf
	v_add_f32_dpp v24, v24, v24 row_half_mirror row_mask:0xf bank_mask:0xf
	v_add_f32_dpp v26, v26, v26 row_half_mirror row_mask:0xf bank_mask:0xf
	v_add_f32_dpp v28, v28, v28 row_half_mirror row_mask:0xf bank_mask:0xf
	v_pk_fma_f32 v[6:7], v[102:103], v[22:23], v[30:31] op_sel_hi:[1,0,1] neg_lo:[0,1,0] neg_hi:[0,1,0]
	v_pk_fma_f32 v[14:15], v[102:103], v[24:25], v[38:39] op_sel_hi:[1,0,1] neg_lo:[0,1,0] neg_hi:[0,1,0]
	v_pk_fma_f32 v[8:9], v[104:105], v[22:23], v[32:33] op_sel_hi:[1,0,1] neg_lo:[0,1,0] neg_hi:[0,1,0]
	v_pk_fma_f32 v[16:17], v[104:105], v[24:25], v[40:41] op_sel_hi:[1,0,1] neg_lo:[0,1,0] neg_hi:[0,1,0]
	v_cvt_pk_f16_f32 v46, v26, v28
	v_pk_mul_f32 v[26:27], v[6:7], v[118:119]
	v_pk_mul_f32 v[28:29], v[14:15], v[118:119]
	v_pk_fma_f32 v[10:11], v[106:107], v[22:23], v[34:35] op_sel_hi:[1,0,1] neg_lo:[0,1,0] neg_hi:[0,1,0]
	v_pk_fma_f32 v[18:19], v[106:107], v[24:25], v[42:43] op_sel_hi:[1,0,1] neg_lo:[0,1,0] neg_hi:[0,1,0]
	v_pk_fma_f32 v[26:27], v[8:9], v[120:121], v[26:27]
	v_pk_fma_f32 v[28:29], v[16:17], v[120:121], v[28:29]
	v_pk_fma_f32 v[12:13], v[108:109], v[22:23], v[36:37] op_sel_hi:[1,0,1] neg_lo:[0,1,0] neg_hi:[0,1,0]
	v_pk_fma_f32 v[20:21], v[108:109], v[24:25], v[44:45] op_sel_hi:[1,0,1] neg_lo:[0,1,0] neg_hi:[0,1,0]
	v_pk_fma_f32 v[26:27], v[10:11], v[122:123], v[26:27]
	v_pk_fma_f32 v[28:29], v[18:19], v[122:123], v[28:29]
	ds_write_b32 v49, v46 offset:0
	v_pk_fma_f32 v[26:27], v[12:13], v[124:125], v[26:27]
	v_pk_fma_f32 v[28:29], v[20:21], v[124:125], v[28:29]
	s_waitcnt lgkmcnt(1)
	v_pk_mul_f32 v[22:23], v[6:7], v[52:53]
	v_pk_mul_f32 v[24:25], v[14:15], v[52:53]
	ds_read_b128 v[94:97], v47 offset:768
	v_add_f32_e32 v26, v26, v27
	v_add_f32_e32 v28, v28, v29
	ds_read_b128 v[98:101], v47 offset:784
	v_pk_mul_f32 v[30:31], v[68:69], v[92:93] op_sel_hi:[1,0]
	v_pk_mul_f32 v[38:39], v[68:69], v[92:93] op_sel:[0,1]
	ds_read_b128 v[110:113], v47 offset:8960
	v_pk_fma_f32 v[22:23], v[8:9], v[54:55], v[22:23]
	v_pk_fma_f32 v[24:25], v[16:17], v[54:55], v[24:25]
	ds_read_b128 v[114:117], v47 offset:8976
	v_pk_mul_f32 v[32:33], v[70:71], v[92:93] op_sel_hi:[1,0]
	v_pk_mul_f32 v[40:41], v[70:71], v[92:93] op_sel:[0,1]
	ds_read_b64 v[134:135], v48 offset:768
	v_pk_fma_f32 v[22:23], v[10:11], v[56:57], v[22:23]
	v_pk_fma_f32 v[24:25], v[18:19], v[56:57], v[24:25]
	ds_read_b128 v[126:129], v47 offset:17152
	v_pk_mul_f32 v[34:35], v[72:73], v[92:93] op_sel_hi:[1,0]
	v_pk_mul_f32 v[42:43], v[72:73], v[92:93] op_sel:[0,1]
	ds_read_b128 v[130:133], v47 offset:17168
	v_pk_fma_f32 v[22:23], v[12:13], v[58:59], v[22:23]
	v_pk_fma_f32 v[24:25], v[20:21], v[58:59], v[24:25]
	ds_read_b128 v[102:105], v47 offset:4864
	v_pk_mul_f32 v[36:37], v[74:75], v[92:93] op_sel_hi:[1,0]
	v_pk_mul_f32 v[44:45], v[74:75], v[92:93] op_sel:[0,1]
	ds_read_b128 v[106:109], v47 offset:4880
	v_add_f32_e32 v22, v22, v23
	v_add_f32_e32 v24, v24, v25
	ds_read_b128 v[118:121], v47 offset:13056
	v_pk_fma_f32 v[30:31], v[84:85], v[6:7], v[30:31]
	v_pk_fma_f32 v[38:39], v[84:85], v[14:15], v[38:39]
	ds_read_b128 v[122:125], v47 offset:13072
	v_pk_fma_f32 v[32:33], v[86:87], v[8:9], v[32:33]
	v_pk_fma_f32 v[40:41], v[86:87], v[16:17], v[40:41]
	v_add_f32_dpp v22, v22, v22 quad_perm:[1,0,3,2] row_mask:0xf bank_mask:0xf
	v_add_f32_dpp v24, v24, v24 quad_perm:[1,0,3,2] row_mask:0xf bank_mask:0xf
	v_add_f32_dpp v26, v26, v26 quad_perm:[1,0,3,2] row_mask:0xf bank_mask:0xf
	v_add_f32_dpp v28, v28, v28 quad_perm:[1,0,3,2] row_mask:0xf bank_mask:0xf
	v_pk_fma_f32 v[34:35], v[88:89], v[10:11], v[34:35]
	v_pk_fma_f32 v[42:43], v[88:89], v[18:19], v[42:43]
	v_add_f32_dpp v22, v22, v22 quad_perm:[2,3,0,1] row_mask:0xf bank_mask:0xf
	v_add_f32_dpp v24, v24, v24 quad_perm:[2,3,0,1] row_mask:0xf bank_mask:0xf
	v_add_f32_dpp v26, v26, v26 quad_perm:[2,3,0,1] row_mask:0xf bank_mask:0xf
	v_add_f32_dpp v28, v28, v28 quad_perm:[2,3,0,1] row_mask:0xf bank_mask:0xf
	v_pk_fma_f32 v[36:37], v[90:91], v[12:13], v[36:37]
	v_pk_fma_f32 v[44:45], v[90:91], v[20:21], v[44:45]
	v_add_f32_dpp v22, v22, v22 row_half_mirror row_mask:0xf bank_mask:0xf
	v_add_f32_dpp v24, v24, v24 row_half_mirror row_mask:0xf bank_mask:0xf
	v_add_f32_dpp v26, v26, v26 row_half_mirror row_mask:0xf bank_mask:0xf
	v_add_f32_dpp v28, v28, v28 row_half_mirror row_mask:0xf bank_mask:0xf
	v_pk_fma_f32 v[6:7], v[60:61], v[22:23], v[30:31] op_sel_hi:[1,0,1] neg_lo:[0,1,0] neg_hi:[0,1,0]
	v_pk_fma_f32 v[14:15], v[60:61], v[24:25], v[38:39] op_sel_hi:[1,0,1] neg_lo:[0,1,0] neg_hi:[0,1,0]
	v_pk_fma_f32 v[8:9], v[62:63], v[22:23], v[32:33] op_sel_hi:[1,0,1] neg_lo:[0,1,0] neg_hi:[0,1,0]
	v_pk_fma_f32 v[16:17], v[62:63], v[24:25], v[40:41] op_sel_hi:[1,0,1] neg_lo:[0,1,0] neg_hi:[0,1,0]
	v_cvt_pk_f16_f32 v46, v26, v28
	v_pk_mul_f32 v[26:27], v[6:7], v[76:77]
	v_pk_mul_f32 v[28:29], v[14:15], v[76:77]
	v_pk_fma_f32 v[10:11], v[64:65], v[22:23], v[34:35] op_sel_hi:[1,0,1] neg_lo:[0,1,0] neg_hi:[0,1,0]
	v_pk_fma_f32 v[18:19], v[64:65], v[24:25], v[42:43] op_sel_hi:[1,0,1] neg_lo:[0,1,0] neg_hi:[0,1,0]
	v_pk_fma_f32 v[26:27], v[8:9], v[78:79], v[26:27]
	v_pk_fma_f32 v[28:29], v[16:17], v[78:79], v[28:29]
	v_pk_fma_f32 v[12:13], v[66:67], v[22:23], v[36:37] op_sel_hi:[1,0,1] neg_lo:[0,1,0] neg_hi:[0,1,0]
	v_pk_fma_f32 v[20:21], v[66:67], v[24:25], v[44:45] op_sel_hi:[1,0,1] neg_lo:[0,1,0] neg_hi:[0,1,0]
	v_pk_fma_f32 v[26:27], v[10:11], v[80:81], v[26:27]
	v_pk_fma_f32 v[28:29], v[18:19], v[80:81], v[28:29]
	ds_write_b32 v49, v46 offset:128
	v_pk_fma_f32 v[26:27], v[12:13], v[82:83], v[26:27]
	v_pk_fma_f32 v[28:29], v[20:21], v[82:83], v[28:29]
	s_waitcnt lgkmcnt(1)
	v_pk_mul_f32 v[22:23], v[6:7], v[94:95]
	v_pk_mul_f32 v[24:25], v[14:15], v[94:95]
	ds_read_b128 v[52:55], v47 offset:1024
	v_add_f32_e32 v26, v26, v27
	v_add_f32_e32 v28, v28, v29
	ds_read_b128 v[56:59], v47 offset:1040
	v_pk_mul_f32 v[30:31], v[110:111], v[134:135] op_sel_hi:[1,0]
	v_pk_mul_f32 v[38:39], v[110:111], v[134:135] op_sel:[0,1]
	ds_read_b128 v[68:71], v47 offset:9216
	v_pk_fma_f32 v[22:23], v[8:9], v[96:97], v[22:23]
	v_pk_fma_f32 v[24:25], v[16:17], v[96:97], v[24:25]
	ds_read_b128 v[72:75], v47 offset:9232
	v_pk_mul_f32 v[32:33], v[112:113], v[134:135] op_sel_hi:[1,0]
	v_pk_mul_f32 v[40:41], v[112:113], v[134:135] op_sel:[0,1]
	ds_read_b64 v[92:93], v48 offset:1024
	v_pk_fma_f32 v[22:23], v[10:11], v[98:99], v[22:23]
	v_pk_fma_f32 v[24:25], v[18:19], v[98:99], v[24:25]
	ds_read_b128 v[84:87], v47 offset:17408
	v_pk_mul_f32 v[34:35], v[114:115], v[134:135] op_sel_hi:[1,0]
	v_pk_mul_f32 v[42:43], v[114:115], v[134:135] op_sel:[0,1]
	ds_read_b128 v[88:91], v47 offset:17424
	v_pk_fma_f32 v[22:23], v[12:13], v[100:101], v[22:23]
	v_pk_fma_f32 v[24:25], v[20:21], v[100:101], v[24:25]
	ds_read_b128 v[60:63], v47 offset:5120
	v_pk_mul_f32 v[36:37], v[116:117], v[134:135] op_sel_hi:[1,0]
	v_pk_mul_f32 v[44:45], v[116:117], v[134:135] op_sel:[0,1]
	ds_read_b128 v[64:67], v47 offset:5136
	v_add_f32_e32 v22, v22, v23
	v_add_f32_e32 v24, v24, v25
	ds_read_b128 v[76:79], v47 offset:13312
	v_pk_fma_f32 v[30:31], v[126:127], v[6:7], v[30:31]
	v_pk_fma_f32 v[38:39], v[126:127], v[14:15], v[38:39]
	ds_read_b128 v[80:83], v47 offset:13328
	v_pk_fma_f32 v[32:33], v[128:129], v[8:9], v[32:33]
	v_pk_fma_f32 v[40:41], v[128:129], v[16:17], v[40:41]
	v_add_f32_dpp v22, v22, v22 quad_perm:[1,0,3,2] row_mask:0xf bank_mask:0xf
	v_add_f32_dpp v24, v24, v24 quad_perm:[1,0,3,2] row_mask:0xf bank_mask:0xf
	v_add_f32_dpp v26, v26, v26 quad_perm:[1,0,3,2] row_mask:0xf bank_mask:0xf
	v_add_f32_dpp v28, v28, v28 quad_perm:[1,0,3,2] row_mask:0xf bank_mask:0xf
	v_pk_fma_f32 v[34:35], v[130:131], v[10:11], v[34:35]
	v_pk_fma_f32 v[42:43], v[130:131], v[18:19], v[42:43]
	v_add_f32_dpp v22, v22, v22 quad_perm:[2,3,0,1] row_mask:0xf bank_mask:0xf
	v_add_f32_dpp v24, v24, v24 quad_perm:[2,3,0,1] row_mask:0xf bank_mask:0xf
	v_add_f32_dpp v26, v26, v26 quad_perm:[2,3,0,1] row_mask:0xf bank_mask:0xf
	v_add_f32_dpp v28, v28, v28 quad_perm:[2,3,0,1] row_mask:0xf bank_mask:0xf
	v_pk_fma_f32 v[36:37], v[132:133], v[12:13], v[36:37]
	v_pk_fma_f32 v[44:45], v[132:133], v[20:21], v[44:45]
	v_add_f32_dpp v22, v22, v22 row_half_mirror row_mask:0xf bank_mask:0xf
	v_add_f32_dpp v24, v24, v24 row_half_mirror row_mask:0xf bank_mask:0xf
	v_add_f32_dpp v26, v26, v26 row_half_mirror row_mask:0xf bank_mask:0xf
	v_add_f32_dpp v28, v28, v28 row_half_mirror row_mask:0xf bank_mask:0xf
	v_pk_fma_f32 v[6:7], v[102:103], v[22:23], v[30:31] op_sel_hi:[1,0,1] neg_lo:[0,1,0] neg_hi:[0,1,0]
	v_pk_fma_f32 v[14:15], v[102:103], v[24:25], v[38:39] op_sel_hi:[1,0,1] neg_lo:[0,1,0] neg_hi:[0,1,0]
	v_pk_fma_f32 v[8:9], v[104:105], v[22:23], v[32:33] op_sel_hi:[1,0,1] neg_lo:[0,1,0] neg_hi:[0,1,0]
	v_pk_fma_f32 v[16:17], v[104:105], v[24:25], v[40:41] op_sel_hi:[1,0,1] neg_lo:[0,1,0] neg_hi:[0,1,0]
	v_cvt_pk_f16_f32 v46, v26, v28
	v_pk_mul_f32 v[26:27], v[6:7], v[118:119]
	v_pk_mul_f32 v[28:29], v[14:15], v[118:119]
	v_pk_fma_f32 v[10:11], v[106:107], v[22:23], v[34:35] op_sel_hi:[1,0,1] neg_lo:[0,1,0] neg_hi:[0,1,0]
	v_pk_fma_f32 v[18:19], v[106:107], v[24:25], v[42:43] op_sel_hi:[1,0,1] neg_lo:[0,1,0] neg_hi:[0,1,0]
	v_pk_fma_f32 v[26:27], v[8:9], v[120:121], v[26:27]
	v_pk_fma_f32 v[28:29], v[16:17], v[120:121], v[28:29]
	v_pk_fma_f32 v[12:13], v[108:109], v[22:23], v[36:37] op_sel_hi:[1,0,1] neg_lo:[0,1,0] neg_hi:[0,1,0]
	v_pk_fma_f32 v[20:21], v[108:109], v[24:25], v[44:45] op_sel_hi:[1,0,1] neg_lo:[0,1,0] neg_hi:[0,1,0]
	v_pk_fma_f32 v[26:27], v[10:11], v[122:123], v[26:27]
	v_pk_fma_f32 v[28:29], v[18:19], v[122:123], v[28:29]
	ds_write_b32 v49, v46 offset:256
	v_pk_fma_f32 v[26:27], v[12:13], v[124:125], v[26:27]
	v_pk_fma_f32 v[28:29], v[20:21], v[124:125], v[28:29]
	s_waitcnt lgkmcnt(1)
	v_pk_mul_f32 v[22:23], v[6:7], v[52:53]
	v_pk_mul_f32 v[24:25], v[14:15], v[52:53]
	ds_read_b128 v[94:97], v47 offset:1280
	v_add_f32_e32 v26, v26, v27
	v_add_f32_e32 v28, v28, v29
	ds_read_b128 v[98:101], v47 offset:1296
	v_pk_mul_f32 v[30:31], v[68:69], v[92:93] op_sel_hi:[1,0]
	v_pk_mul_f32 v[38:39], v[68:69], v[92:93] op_sel:[0,1]
	ds_read_b128 v[110:113], v47 offset:9472
	v_pk_fma_f32 v[22:23], v[8:9], v[54:55], v[22:23]
	v_pk_fma_f32 v[24:25], v[16:17], v[54:55], v[24:25]
	ds_read_b128 v[114:117], v47 offset:9488
	v_pk_mul_f32 v[32:33], v[70:71], v[92:93] op_sel_hi:[1,0]
	v_pk_mul_f32 v[40:41], v[70:71], v[92:93] op_sel:[0,1]
	ds_read_b64 v[134:135], v48 offset:1280
	v_pk_fma_f32 v[22:23], v[10:11], v[56:57], v[22:23]
	v_pk_fma_f32 v[24:25], v[18:19], v[56:57], v[24:25]
	ds_read_b128 v[126:129], v47 offset:17664
	v_pk_mul_f32 v[34:35], v[72:73], v[92:93] op_sel_hi:[1,0]
	v_pk_mul_f32 v[42:43], v[72:73], v[92:93] op_sel:[0,1]
	ds_read_b128 v[130:133], v47 offset:17680
	v_pk_fma_f32 v[22:23], v[12:13], v[58:59], v[22:23]
	v_pk_fma_f32 v[24:25], v[20:21], v[58:59], v[24:25]
	ds_read_b128 v[102:105], v47 offset:5376
	v_pk_mul_f32 v[36:37], v[74:75], v[92:93] op_sel_hi:[1,0]
	v_pk_mul_f32 v[44:45], v[74:75], v[92:93] op_sel:[0,1]
	ds_read_b128 v[106:109], v47 offset:5392
	v_add_f32_e32 v22, v22, v23
	v_add_f32_e32 v24, v24, v25
	ds_read_b128 v[118:121], v47 offset:13568
	v_pk_fma_f32 v[30:31], v[84:85], v[6:7], v[30:31]
	v_pk_fma_f32 v[38:39], v[84:85], v[14:15], v[38:39]
	ds_read_b128 v[122:125], v47 offset:13584
	v_pk_fma_f32 v[32:33], v[86:87], v[8:9], v[32:33]
	v_pk_fma_f32 v[40:41], v[86:87], v[16:17], v[40:41]
	v_add_f32_dpp v22, v22, v22 quad_perm:[1,0,3,2] row_mask:0xf bank_mask:0xf
	v_add_f32_dpp v24, v24, v24 quad_perm:[1,0,3,2] row_mask:0xf bank_mask:0xf
	v_add_f32_dpp v26, v26, v26 quad_perm:[1,0,3,2] row_mask:0xf bank_mask:0xf
	v_add_f32_dpp v28, v28, v28 quad_perm:[1,0,3,2] row_mask:0xf bank_mask:0xf
	v_pk_fma_f32 v[34:35], v[88:89], v[10:11], v[34:35]
	v_pk_fma_f32 v[42:43], v[88:89], v[18:19], v[42:43]
	v_add_f32_dpp v22, v22, v22 quad_perm:[2,3,0,1] row_mask:0xf bank_mask:0xf
	v_add_f32_dpp v24, v24, v24 quad_perm:[2,3,0,1] row_mask:0xf bank_mask:0xf
	v_add_f32_dpp v26, v26, v26 quad_perm:[2,3,0,1] row_mask:0xf bank_mask:0xf
	v_add_f32_dpp v28, v28, v28 quad_perm:[2,3,0,1] row_mask:0xf bank_mask:0xf
	v_pk_fma_f32 v[36:37], v[90:91], v[12:13], v[36:37]
	v_pk_fma_f32 v[44:45], v[90:91], v[20:21], v[44:45]
	v_add_f32_dpp v22, v22, v22 row_half_mirror row_mask:0xf bank_mask:0xf
	v_add_f32_dpp v24, v24, v24 row_half_mirror row_mask:0xf bank_mask:0xf
	v_add_f32_dpp v26, v26, v26 row_half_mirror row_mask:0xf bank_mask:0xf
	v_add_f32_dpp v28, v28, v28 row_half_mirror row_mask:0xf bank_mask:0xf
	v_pk_fma_f32 v[6:7], v[60:61], v[22:23], v[30:31] op_sel_hi:[1,0,1] neg_lo:[0,1,0] neg_hi:[0,1,0]
	v_pk_fma_f32 v[14:15], v[60:61], v[24:25], v[38:39] op_sel_hi:[1,0,1] neg_lo:[0,1,0] neg_hi:[0,1,0]
	v_pk_fma_f32 v[8:9], v[62:63], v[22:23], v[32:33] op_sel_hi:[1,0,1] neg_lo:[0,1,0] neg_hi:[0,1,0]
	v_pk_fma_f32 v[16:17], v[62:63], v[24:25], v[40:41] op_sel_hi:[1,0,1] neg_lo:[0,1,0] neg_hi:[0,1,0]
	v_cvt_pk_f16_f32 v46, v26, v28
	v_pk_mul_f32 v[26:27], v[6:7], v[76:77]
	v_pk_mul_f32 v[28:29], v[14:15], v[76:77]
	v_pk_fma_f32 v[10:11], v[64:65], v[22:23], v[34:35] op_sel_hi:[1,0,1] neg_lo:[0,1,0] neg_hi:[0,1,0]
	v_pk_fma_f32 v[18:19], v[64:65], v[24:25], v[42:43] op_sel_hi:[1,0,1] neg_lo:[0,1,0] neg_hi:[0,1,0]
	v_pk_fma_f32 v[26:27], v[8:9], v[78:79], v[26:27]
	v_pk_fma_f32 v[28:29], v[16:17], v[78:79], v[28:29]
	v_pk_fma_f32 v[12:13], v[66:67], v[22:23], v[36:37] op_sel_hi:[1,0,1] neg_lo:[0,1,0] neg_hi:[0,1,0]
	v_pk_fma_f32 v[20:21], v[66:67], v[24:25], v[44:45] op_sel_hi:[1,0,1] neg_lo:[0,1,0] neg_hi:[0,1,0]
	v_pk_fma_f32 v[26:27], v[10:11], v[80:81], v[26:27]
	v_pk_fma_f32 v[28:29], v[18:19], v[80:81], v[28:29]
	ds_write_b32 v49, v46 offset:384
	v_pk_fma_f32 v[26:27], v[12:13], v[82:83], v[26:27]
	v_pk_fma_f32 v[28:29], v[20:21], v[82:83], v[28:29]
	s_waitcnt lgkmcnt(1)
	v_pk_mul_f32 v[22:23], v[6:7], v[94:95]
	v_pk_mul_f32 v[24:25], v[14:15], v[94:95]
	ds_read_b128 v[52:55], v47 offset:1536
	v_add_f32_e32 v26, v26, v27
	v_add_f32_e32 v28, v28, v29
	ds_read_b128 v[56:59], v47 offset:1552
	v_pk_mul_f32 v[30:31], v[110:111], v[134:135] op_sel_hi:[1,0]
	v_pk_mul_f32 v[38:39], v[110:111], v[134:135] op_sel:[0,1]
	ds_read_b128 v[68:71], v47 offset:9728
	v_pk_fma_f32 v[22:23], v[8:9], v[96:97], v[22:23]
	v_pk_fma_f32 v[24:25], v[16:17], v[96:97], v[24:25]
	ds_read_b128 v[72:75], v47 offset:9744
	v_pk_mul_f32 v[32:33], v[112:113], v[134:135] op_sel_hi:[1,0]
	v_pk_mul_f32 v[40:41], v[112:113], v[134:135] op_sel:[0,1]
	ds_read_b64 v[92:93], v48 offset:1536
	v_pk_fma_f32 v[22:23], v[10:11], v[98:99], v[22:23]
	v_pk_fma_f32 v[24:25], v[18:19], v[98:99], v[24:25]
	ds_read_b128 v[84:87], v47 offset:17920
	v_pk_mul_f32 v[34:35], v[114:115], v[134:135] op_sel_hi:[1,0]
	v_pk_mul_f32 v[42:43], v[114:115], v[134:135] op_sel:[0,1]
	ds_read_b128 v[88:91], v47 offset:17936
	v_pk_fma_f32 v[22:23], v[12:13], v[100:101], v[22:23]
	v_pk_fma_f32 v[24:25], v[20:21], v[100:101], v[24:25]
	ds_read_b128 v[60:63], v47 offset:5632
	v_pk_mul_f32 v[36:37], v[116:117], v[134:135] op_sel_hi:[1,0]
	v_pk_mul_f32 v[44:45], v[116:117], v[134:135] op_sel:[0,1]
	ds_read_b128 v[64:67], v47 offset:5648
	v_add_f32_e32 v22, v22, v23
	v_add_f32_e32 v24, v24, v25
	ds_read_b128 v[76:79], v47 offset:13824
	v_pk_fma_f32 v[30:31], v[126:127], v[6:7], v[30:31]
	v_pk_fma_f32 v[38:39], v[126:127], v[14:15], v[38:39]
	ds_read_b128 v[80:83], v47 offset:13840
	v_pk_fma_f32 v[32:33], v[128:129], v[8:9], v[32:33]
	v_pk_fma_f32 v[40:41], v[128:129], v[16:17], v[40:41]
	v_add_f32_dpp v22, v22, v22 quad_perm:[1,0,3,2] row_mask:0xf bank_mask:0xf
	v_add_f32_dpp v24, v24, v24 quad_perm:[1,0,3,2] row_mask:0xf bank_mask:0xf
	v_add_f32_dpp v26, v26, v26 quad_perm:[1,0,3,2] row_mask:0xf bank_mask:0xf
	v_add_f32_dpp v28, v28, v28 quad_perm:[1,0,3,2] row_mask:0xf bank_mask:0xf
	v_pk_fma_f32 v[34:35], v[130:131], v[10:11], v[34:35]
	v_pk_fma_f32 v[42:43], v[130:131], v[18:19], v[42:43]
	v_add_f32_dpp v22, v22, v22 quad_perm:[2,3,0,1] row_mask:0xf bank_mask:0xf
	v_add_f32_dpp v24, v24, v24 quad_perm:[2,3,0,1] row_mask:0xf bank_mask:0xf
	v_add_f32_dpp v26, v26, v26 quad_perm:[2,3,0,1] row_mask:0xf bank_mask:0xf
	v_add_f32_dpp v28, v28, v28 quad_perm:[2,3,0,1] row_mask:0xf bank_mask:0xf
	v_pk_fma_f32 v[36:37], v[132:133], v[12:13], v[36:37]
	v_pk_fma_f32 v[44:45], v[132:133], v[20:21], v[44:45]
	v_add_f32_dpp v22, v22, v22 row_half_mirror row_mask:0xf bank_mask:0xf
	v_add_f32_dpp v24, v24, v24 row_half_mirror row_mask:0xf bank_mask:0xf
	v_add_f32_dpp v26, v26, v26 row_half_mirror row_mask:0xf bank_mask:0xf
	v_add_f32_dpp v28, v28, v28 row_half_mirror row_mask:0xf bank_mask:0xf
	v_pk_fma_f32 v[6:7], v[102:103], v[22:23], v[30:31] op_sel_hi:[1,0,1] neg_lo:[0,1,0] neg_hi:[0,1,0]
	v_pk_fma_f32 v[14:15], v[102:103], v[24:25], v[38:39] op_sel_hi:[1,0,1] neg_lo:[0,1,0] neg_hi:[0,1,0]
	v_pk_fma_f32 v[8:9], v[104:105], v[22:23], v[32:33] op_sel_hi:[1,0,1] neg_lo:[0,1,0] neg_hi:[0,1,0]
	v_pk_fma_f32 v[16:17], v[104:105], v[24:25], v[40:41] op_sel_hi:[1,0,1] neg_lo:[0,1,0] neg_hi:[0,1,0]
	v_cvt_pk_f16_f32 v46, v26, v28
	v_pk_mul_f32 v[26:27], v[6:7], v[118:119]
	v_pk_mul_f32 v[28:29], v[14:15], v[118:119]
	v_pk_fma_f32 v[10:11], v[106:107], v[22:23], v[34:35] op_sel_hi:[1,0,1] neg_lo:[0,1,0] neg_hi:[0,1,0]
	v_pk_fma_f32 v[18:19], v[106:107], v[24:25], v[42:43] op_sel_hi:[1,0,1] neg_lo:[0,1,0] neg_hi:[0,1,0]
	v_pk_fma_f32 v[26:27], v[8:9], v[120:121], v[26:27]
	v_pk_fma_f32 v[28:29], v[16:17], v[120:121], v[28:29]
	v_pk_fma_f32 v[12:13], v[108:109], v[22:23], v[36:37] op_sel_hi:[1,0,1] neg_lo:[0,1,0] neg_hi:[0,1,0]
	v_pk_fma_f32 v[20:21], v[108:109], v[24:25], v[44:45] op_sel_hi:[1,0,1] neg_lo:[0,1,0] neg_hi:[0,1,0]
	v_pk_fma_f32 v[26:27], v[10:11], v[122:123], v[26:27]
	v_pk_fma_f32 v[28:29], v[18:19], v[122:123], v[28:29]
	ds_write_b32 v49, v46 offset:512
	v_pk_fma_f32 v[26:27], v[12:13], v[124:125], v[26:27]
	v_pk_fma_f32 v[28:29], v[20:21], v[124:125], v[28:29]
	s_waitcnt lgkmcnt(1)
	v_pk_mul_f32 v[22:23], v[6:7], v[52:53]
	v_pk_mul_f32 v[24:25], v[14:15], v[52:53]
	ds_read_b128 v[94:97], v47 offset:1792
	v_add_f32_e32 v26, v26, v27
	v_add_f32_e32 v28, v28, v29
	ds_read_b128 v[98:101], v47 offset:1808
	v_pk_mul_f32 v[30:31], v[68:69], v[92:93] op_sel_hi:[1,0]
	v_pk_mul_f32 v[38:39], v[68:69], v[92:93] op_sel:[0,1]
	ds_read_b128 v[110:113], v47 offset:9984
	v_pk_fma_f32 v[22:23], v[8:9], v[54:55], v[22:23]
	v_pk_fma_f32 v[24:25], v[16:17], v[54:55], v[24:25]
	ds_read_b128 v[114:117], v47 offset:10000
	v_pk_mul_f32 v[32:33], v[70:71], v[92:93] op_sel_hi:[1,0]
	v_pk_mul_f32 v[40:41], v[70:71], v[92:93] op_sel:[0,1]
	ds_read_b64 v[134:135], v48 offset:1792
	v_pk_fma_f32 v[22:23], v[10:11], v[56:57], v[22:23]
	v_pk_fma_f32 v[24:25], v[18:19], v[56:57], v[24:25]
	ds_read_b128 v[126:129], v47 offset:18176
	v_pk_mul_f32 v[34:35], v[72:73], v[92:93] op_sel_hi:[1,0]
	v_pk_mul_f32 v[42:43], v[72:73], v[92:93] op_sel:[0,1]
	ds_read_b128 v[130:133], v47 offset:18192
	v_pk_fma_f32 v[22:23], v[12:13], v[58:59], v[22:23]
	v_pk_fma_f32 v[24:25], v[20:21], v[58:59], v[24:25]
	ds_read_b128 v[102:105], v47 offset:5888
	v_pk_mul_f32 v[36:37], v[74:75], v[92:93] op_sel_hi:[1,0]
	v_pk_mul_f32 v[44:45], v[74:75], v[92:93] op_sel:[0,1]
	ds_read_b128 v[106:109], v47 offset:5904
	v_add_f32_e32 v22, v22, v23
	v_add_f32_e32 v24, v24, v25
	ds_read_b128 v[118:121], v47 offset:14080
	v_pk_fma_f32 v[30:31], v[84:85], v[6:7], v[30:31]
	v_pk_fma_f32 v[38:39], v[84:85], v[14:15], v[38:39]
	ds_read_b128 v[122:125], v47 offset:14096
	v_pk_fma_f32 v[32:33], v[86:87], v[8:9], v[32:33]
	v_pk_fma_f32 v[40:41], v[86:87], v[16:17], v[40:41]
	v_add_f32_dpp v22, v22, v22 quad_perm:[1,0,3,2] row_mask:0xf bank_mask:0xf
	v_add_f32_dpp v24, v24, v24 quad_perm:[1,0,3,2] row_mask:0xf bank_mask:0xf
	v_add_f32_dpp v26, v26, v26 quad_perm:[1,0,3,2] row_mask:0xf bank_mask:0xf
	v_add_f32_dpp v28, v28, v28 quad_perm:[1,0,3,2] row_mask:0xf bank_mask:0xf
	v_pk_fma_f32 v[34:35], v[88:89], v[10:11], v[34:35]
	v_pk_fma_f32 v[42:43], v[88:89], v[18:19], v[42:43]
	v_add_f32_dpp v22, v22, v22 quad_perm:[2,3,0,1] row_mask:0xf bank_mask:0xf
	v_add_f32_dpp v24, v24, v24 quad_perm:[2,3,0,1] row_mask:0xf bank_mask:0xf
	v_add_f32_dpp v26, v26, v26 quad_perm:[2,3,0,1] row_mask:0xf bank_mask:0xf
	v_add_f32_dpp v28, v28, v28 quad_perm:[2,3,0,1] row_mask:0xf bank_mask:0xf
	v_pk_fma_f32 v[36:37], v[90:91], v[12:13], v[36:37]
	v_pk_fma_f32 v[44:45], v[90:91], v[20:21], v[44:45]
	v_add_f32_dpp v22, v22, v22 row_half_mirror row_mask:0xf bank_mask:0xf
	v_add_f32_dpp v24, v24, v24 row_half_mirror row_mask:0xf bank_mask:0xf
	v_add_f32_dpp v26, v26, v26 row_half_mirror row_mask:0xf bank_mask:0xf
	v_add_f32_dpp v28, v28, v28 row_half_mirror row_mask:0xf bank_mask:0xf
	v_pk_fma_f32 v[6:7], v[60:61], v[22:23], v[30:31] op_sel_hi:[1,0,1] neg_lo:[0,1,0] neg_hi:[0,1,0]
	v_pk_fma_f32 v[14:15], v[60:61], v[24:25], v[38:39] op_sel_hi:[1,0,1] neg_lo:[0,1,0] neg_hi:[0,1,0]
	v_pk_fma_f32 v[8:9], v[62:63], v[22:23], v[32:33] op_sel_hi:[1,0,1] neg_lo:[0,1,0] neg_hi:[0,1,0]
	v_pk_fma_f32 v[16:17], v[62:63], v[24:25], v[40:41] op_sel_hi:[1,0,1] neg_lo:[0,1,0] neg_hi:[0,1,0]
	v_cvt_pk_f16_f32 v46, v26, v28
	v_pk_mul_f32 v[26:27], v[6:7], v[76:77]
	v_pk_mul_f32 v[28:29], v[14:15], v[76:77]
	v_pk_fma_f32 v[10:11], v[64:65], v[22:23], v[34:35] op_sel_hi:[1,0,1] neg_lo:[0,1,0] neg_hi:[0,1,0]
	v_pk_fma_f32 v[18:19], v[64:65], v[24:25], v[42:43] op_sel_hi:[1,0,1] neg_lo:[0,1,0] neg_hi:[0,1,0]
	v_pk_fma_f32 v[26:27], v[8:9], v[78:79], v[26:27]
	v_pk_fma_f32 v[28:29], v[16:17], v[78:79], v[28:29]
	v_pk_fma_f32 v[12:13], v[66:67], v[22:23], v[36:37] op_sel_hi:[1,0,1] neg_lo:[0,1,0] neg_hi:[0,1,0]
	v_pk_fma_f32 v[20:21], v[66:67], v[24:25], v[44:45] op_sel_hi:[1,0,1] neg_lo:[0,1,0] neg_hi:[0,1,0]
	v_pk_fma_f32 v[26:27], v[10:11], v[80:81], v[26:27]
	v_pk_fma_f32 v[28:29], v[18:19], v[80:81], v[28:29]
	ds_write_b32 v49, v46 offset:640
	v_pk_fma_f32 v[26:27], v[12:13], v[82:83], v[26:27]
	v_pk_fma_f32 v[28:29], v[20:21], v[82:83], v[28:29]
	s_waitcnt lgkmcnt(1)
	v_pk_mul_f32 v[22:23], v[6:7], v[94:95]
	v_pk_mul_f32 v[24:25], v[14:15], v[94:95]
	ds_read_b128 v[52:55], v47 offset:2048
	v_add_f32_e32 v26, v26, v27
	v_add_f32_e32 v28, v28, v29
	ds_read_b128 v[56:59], v47 offset:2064
	v_pk_mul_f32 v[30:31], v[110:111], v[134:135] op_sel_hi:[1,0]
	v_pk_mul_f32 v[38:39], v[110:111], v[134:135] op_sel:[0,1]
	ds_read_b128 v[68:71], v47 offset:10240
	v_pk_fma_f32 v[22:23], v[8:9], v[96:97], v[22:23]
	v_pk_fma_f32 v[24:25], v[16:17], v[96:97], v[24:25]
	ds_read_b128 v[72:75], v47 offset:10256
	v_pk_mul_f32 v[32:33], v[112:113], v[134:135] op_sel_hi:[1,0]
	v_pk_mul_f32 v[40:41], v[112:113], v[134:135] op_sel:[0,1]
	ds_read_b64 v[92:93], v48 offset:2048
	v_pk_fma_f32 v[22:23], v[10:11], v[98:99], v[22:23]
	v_pk_fma_f32 v[24:25], v[18:19], v[98:99], v[24:25]
	ds_read_b128 v[84:87], v47 offset:18432
	v_pk_mul_f32 v[34:35], v[114:115], v[134:135] op_sel_hi:[1,0]
	v_pk_mul_f32 v[42:43], v[114:115], v[134:135] op_sel:[0,1]
	ds_read_b128 v[88:91], v47 offset:18448
	v_pk_fma_f32 v[22:23], v[12:13], v[100:101], v[22:23]
	v_pk_fma_f32 v[24:25], v[20:21], v[100:101], v[24:25]
	ds_read_b128 v[60:63], v47 offset:6144
	v_pk_mul_f32 v[36:37], v[116:117], v[134:135] op_sel_hi:[1,0]
	v_pk_mul_f32 v[44:45], v[116:117], v[134:135] op_sel:[0,1]
	ds_read_b128 v[64:67], v47 offset:6160
	v_add_f32_e32 v22, v22, v23
	v_add_f32_e32 v24, v24, v25
	ds_read_b128 v[76:79], v47 offset:14336
	v_pk_fma_f32 v[30:31], v[126:127], v[6:7], v[30:31]
	v_pk_fma_f32 v[38:39], v[126:127], v[14:15], v[38:39]
	ds_read_b128 v[80:83], v47 offset:14352
	v_pk_fma_f32 v[32:33], v[128:129], v[8:9], v[32:33]
	v_pk_fma_f32 v[40:41], v[128:129], v[16:17], v[40:41]
	v_add_f32_dpp v22, v22, v22 quad_perm:[1,0,3,2] row_mask:0xf bank_mask:0xf
	v_add_f32_dpp v24, v24, v24 quad_perm:[1,0,3,2] row_mask:0xf bank_mask:0xf
	v_add_f32_dpp v26, v26, v26 quad_perm:[1,0,3,2] row_mask:0xf bank_mask:0xf
	v_add_f32_dpp v28, v28, v28 quad_perm:[1,0,3,2] row_mask:0xf bank_mask:0xf
	v_pk_fma_f32 v[34:35], v[130:131], v[10:11], v[34:35]
	v_pk_fma_f32 v[42:43], v[130:131], v[18:19], v[42:43]
	v_add_f32_dpp v22, v22, v22 quad_perm:[2,3,0,1] row_mask:0xf bank_mask:0xf
	v_add_f32_dpp v24, v24, v24 quad_perm:[2,3,0,1] row_mask:0xf bank_mask:0xf
	v_add_f32_dpp v26, v26, v26 quad_perm:[2,3,0,1] row_mask:0xf bank_mask:0xf
	v_add_f32_dpp v28, v28, v28 quad_perm:[2,3,0,1] row_mask:0xf bank_mask:0xf
	v_pk_fma_f32 v[36:37], v[132:133], v[12:13], v[36:37]
	v_pk_fma_f32 v[44:45], v[132:133], v[20:21], v[44:45]
	v_add_f32_dpp v22, v22, v22 row_half_mirror row_mask:0xf bank_mask:0xf
	v_add_f32_dpp v24, v24, v24 row_half_mirror row_mask:0xf bank_mask:0xf
	v_add_f32_dpp v26, v26, v26 row_half_mirror row_mask:0xf bank_mask:0xf
	v_add_f32_dpp v28, v28, v28 row_half_mirror row_mask:0xf bank_mask:0xf
	v_pk_fma_f32 v[6:7], v[102:103], v[22:23], v[30:31] op_sel_hi:[1,0,1] neg_lo:[0,1,0] neg_hi:[0,1,0]
	v_pk_fma_f32 v[14:15], v[102:103], v[24:25], v[38:39] op_sel_hi:[1,0,1] neg_lo:[0,1,0] neg_hi:[0,1,0]
	v_pk_fma_f32 v[8:9], v[104:105], v[22:23], v[32:33] op_sel_hi:[1,0,1] neg_lo:[0,1,0] neg_hi:[0,1,0]
	v_pk_fma_f32 v[16:17], v[104:105], v[24:25], v[40:41] op_sel_hi:[1,0,1] neg_lo:[0,1,0] neg_hi:[0,1,0]
	v_cvt_pk_f16_f32 v46, v26, v28
	v_pk_mul_f32 v[26:27], v[6:7], v[118:119]
	v_pk_mul_f32 v[28:29], v[14:15], v[118:119]
	v_pk_fma_f32 v[10:11], v[106:107], v[22:23], v[34:35] op_sel_hi:[1,0,1] neg_lo:[0,1,0] neg_hi:[0,1,0]
	v_pk_fma_f32 v[18:19], v[106:107], v[24:25], v[42:43] op_sel_hi:[1,0,1] neg_lo:[0,1,0] neg_hi:[0,1,0]
	v_pk_fma_f32 v[26:27], v[8:9], v[120:121], v[26:27]
	v_pk_fma_f32 v[28:29], v[16:17], v[120:121], v[28:29]
	v_pk_fma_f32 v[12:13], v[108:109], v[22:23], v[36:37] op_sel_hi:[1,0,1] neg_lo:[0,1,0] neg_hi:[0,1,0]
	v_pk_fma_f32 v[20:21], v[108:109], v[24:25], v[44:45] op_sel_hi:[1,0,1] neg_lo:[0,1,0] neg_hi:[0,1,0]
	v_pk_fma_f32 v[26:27], v[10:11], v[122:123], v[26:27]
	v_pk_fma_f32 v[28:29], v[18:19], v[122:123], v[28:29]
	ds_write_b32 v49, v46 offset:768
	v_pk_fma_f32 v[26:27], v[12:13], v[124:125], v[26:27]
	v_pk_fma_f32 v[28:29], v[20:21], v[124:125], v[28:29]
	s_waitcnt lgkmcnt(1)
	v_pk_mul_f32 v[22:23], v[6:7], v[52:53]
	v_pk_mul_f32 v[24:25], v[14:15], v[52:53]
	ds_read_b128 v[94:97], v47 offset:2304
	v_add_f32_e32 v26, v26, v27
	v_add_f32_e32 v28, v28, v29
	ds_read_b128 v[98:101], v47 offset:2320
	v_pk_mul_f32 v[30:31], v[68:69], v[92:93] op_sel_hi:[1,0]
	v_pk_mul_f32 v[38:39], v[68:69], v[92:93] op_sel:[0,1]
	ds_read_b128 v[110:113], v47 offset:10496
	v_pk_fma_f32 v[22:23], v[8:9], v[54:55], v[22:23]
	v_pk_fma_f32 v[24:25], v[16:17], v[54:55], v[24:25]
	ds_read_b128 v[114:117], v47 offset:10512
	v_pk_mul_f32 v[32:33], v[70:71], v[92:93] op_sel_hi:[1,0]
	v_pk_mul_f32 v[40:41], v[70:71], v[92:93] op_sel:[0,1]
	ds_read_b64 v[134:135], v48 offset:2304
	v_pk_fma_f32 v[22:23], v[10:11], v[56:57], v[22:23]
	v_pk_fma_f32 v[24:25], v[18:19], v[56:57], v[24:25]
	ds_read_b128 v[126:129], v47 offset:18688
	v_pk_mul_f32 v[34:35], v[72:73], v[92:93] op_sel_hi:[1,0]
	v_pk_mul_f32 v[42:43], v[72:73], v[92:93] op_sel:[0,1]
	ds_read_b128 v[130:133], v47 offset:18704
	v_pk_fma_f32 v[22:23], v[12:13], v[58:59], v[22:23]
	v_pk_fma_f32 v[24:25], v[20:21], v[58:59], v[24:25]
	ds_read_b128 v[102:105], v47 offset:6400
	v_pk_mul_f32 v[36:37], v[74:75], v[92:93] op_sel_hi:[1,0]
	v_pk_mul_f32 v[44:45], v[74:75], v[92:93] op_sel:[0,1]
	ds_read_b128 v[106:109], v47 offset:6416
	v_add_f32_e32 v22, v22, v23
	v_add_f32_e32 v24, v24, v25
	ds_read_b128 v[118:121], v47 offset:14592
	v_pk_fma_f32 v[30:31], v[84:85], v[6:7], v[30:31]
	v_pk_fma_f32 v[38:39], v[84:85], v[14:15], v[38:39]
	ds_read_b128 v[122:125], v47 offset:14608
	v_pk_fma_f32 v[32:33], v[86:87], v[8:9], v[32:33]
	v_pk_fma_f32 v[40:41], v[86:87], v[16:17], v[40:41]
	v_add_f32_dpp v22, v22, v22 quad_perm:[1,0,3,2] row_mask:0xf bank_mask:0xf
	v_add_f32_dpp v24, v24, v24 quad_perm:[1,0,3,2] row_mask:0xf bank_mask:0xf
	v_add_f32_dpp v26, v26, v26 quad_perm:[1,0,3,2] row_mask:0xf bank_mask:0xf
	v_add_f32_dpp v28, v28, v28 quad_perm:[1,0,3,2] row_mask:0xf bank_mask:0xf
	v_pk_fma_f32 v[34:35], v[88:89], v[10:11], v[34:35]
	v_pk_fma_f32 v[42:43], v[88:89], v[18:19], v[42:43]
	v_add_f32_dpp v22, v22, v22 quad_perm:[2,3,0,1] row_mask:0xf bank_mask:0xf
	v_add_f32_dpp v24, v24, v24 quad_perm:[2,3,0,1] row_mask:0xf bank_mask:0xf
	v_add_f32_dpp v26, v26, v26 quad_perm:[2,3,0,1] row_mask:0xf bank_mask:0xf
	v_add_f32_dpp v28, v28, v28 quad_perm:[2,3,0,1] row_mask:0xf bank_mask:0xf
	v_pk_fma_f32 v[36:37], v[90:91], v[12:13], v[36:37]
	v_pk_fma_f32 v[44:45], v[90:91], v[20:21], v[44:45]
	v_add_f32_dpp v22, v22, v22 row_half_mirror row_mask:0xf bank_mask:0xf
	v_add_f32_dpp v24, v24, v24 row_half_mirror row_mask:0xf bank_mask:0xf
	v_add_f32_dpp v26, v26, v26 row_half_mirror row_mask:0xf bank_mask:0xf
	v_add_f32_dpp v28, v28, v28 row_half_mirror row_mask:0xf bank_mask:0xf
	v_pk_fma_f32 v[6:7], v[60:61], v[22:23], v[30:31] op_sel_hi:[1,0,1] neg_lo:[0,1,0] neg_hi:[0,1,0]
	v_pk_fma_f32 v[14:15], v[60:61], v[24:25], v[38:39] op_sel_hi:[1,0,1] neg_lo:[0,1,0] neg_hi:[0,1,0]
	v_pk_fma_f32 v[8:9], v[62:63], v[22:23], v[32:33] op_sel_hi:[1,0,1] neg_lo:[0,1,0] neg_hi:[0,1,0]
	v_pk_fma_f32 v[16:17], v[62:63], v[24:25], v[40:41] op_sel_hi:[1,0,1] neg_lo:[0,1,0] neg_hi:[0,1,0]
	v_cvt_pk_f16_f32 v46, v26, v28
	v_pk_mul_f32 v[26:27], v[6:7], v[76:77]
	v_pk_mul_f32 v[28:29], v[14:15], v[76:77]
	v_pk_fma_f32 v[10:11], v[64:65], v[22:23], v[34:35] op_sel_hi:[1,0,1] neg_lo:[0,1,0] neg_hi:[0,1,0]
	v_pk_fma_f32 v[18:19], v[64:65], v[24:25], v[42:43] op_sel_hi:[1,0,1] neg_lo:[0,1,0] neg_hi:[0,1,0]
	v_pk_fma_f32 v[26:27], v[8:9], v[78:79], v[26:27]
	v_pk_fma_f32 v[28:29], v[16:17], v[78:79], v[28:29]
	v_pk_fma_f32 v[12:13], v[66:67], v[22:23], v[36:37] op_sel_hi:[1,0,1] neg_lo:[0,1,0] neg_hi:[0,1,0]
	v_pk_fma_f32 v[20:21], v[66:67], v[24:25], v[44:45] op_sel_hi:[1,0,1] neg_lo:[0,1,0] neg_hi:[0,1,0]
	v_pk_fma_f32 v[26:27], v[10:11], v[80:81], v[26:27]
	v_pk_fma_f32 v[28:29], v[18:19], v[80:81], v[28:29]
	ds_write_b32 v49, v46 offset:896
	v_pk_fma_f32 v[26:27], v[12:13], v[82:83], v[26:27]
	v_pk_fma_f32 v[28:29], v[20:21], v[82:83], v[28:29]
	s_waitcnt lgkmcnt(1)
	v_pk_mul_f32 v[22:23], v[6:7], v[94:95]
	v_pk_mul_f32 v[24:25], v[14:15], v[94:95]
	ds_read_b128 v[52:55], v47 offset:2560
	v_add_f32_e32 v26, v26, v27
	v_add_f32_e32 v28, v28, v29
	ds_read_b128 v[56:59], v47 offset:2576
	v_pk_mul_f32 v[30:31], v[110:111], v[134:135] op_sel_hi:[1,0]
	v_pk_mul_f32 v[38:39], v[110:111], v[134:135] op_sel:[0,1]
	ds_read_b128 v[68:71], v47 offset:10752
	v_pk_fma_f32 v[22:23], v[8:9], v[96:97], v[22:23]
	v_pk_fma_f32 v[24:25], v[16:17], v[96:97], v[24:25]
	ds_read_b128 v[72:75], v47 offset:10768
	v_pk_mul_f32 v[32:33], v[112:113], v[134:135] op_sel_hi:[1,0]
	v_pk_mul_f32 v[40:41], v[112:113], v[134:135] op_sel:[0,1]
	ds_read_b64 v[92:93], v48 offset:2560
	v_pk_fma_f32 v[22:23], v[10:11], v[98:99], v[22:23]
	v_pk_fma_f32 v[24:25], v[18:19], v[98:99], v[24:25]
	ds_read_b128 v[84:87], v47 offset:18944
	v_pk_mul_f32 v[34:35], v[114:115], v[134:135] op_sel_hi:[1,0]
	v_pk_mul_f32 v[42:43], v[114:115], v[134:135] op_sel:[0,1]
	ds_read_b128 v[88:91], v47 offset:18960
	v_pk_fma_f32 v[22:23], v[12:13], v[100:101], v[22:23]
	v_pk_fma_f32 v[24:25], v[20:21], v[100:101], v[24:25]
	ds_read_b128 v[60:63], v47 offset:6656
	v_pk_mul_f32 v[36:37], v[116:117], v[134:135] op_sel_hi:[1,0]
	v_pk_mul_f32 v[44:45], v[116:117], v[134:135] op_sel:[0,1]
	ds_read_b128 v[64:67], v47 offset:6672
	v_add_f32_e32 v22, v22, v23
	v_add_f32_e32 v24, v24, v25
	ds_read_b128 v[76:79], v47 offset:14848
	v_pk_fma_f32 v[30:31], v[126:127], v[6:7], v[30:31]
	v_pk_fma_f32 v[38:39], v[126:127], v[14:15], v[38:39]
	ds_read_b128 v[80:83], v47 offset:14864
	v_pk_fma_f32 v[32:33], v[128:129], v[8:9], v[32:33]
	v_pk_fma_f32 v[40:41], v[128:129], v[16:17], v[40:41]
	v_add_f32_dpp v22, v22, v22 quad_perm:[1,0,3,2] row_mask:0xf bank_mask:0xf
	v_add_f32_dpp v24, v24, v24 quad_perm:[1,0,3,2] row_mask:0xf bank_mask:0xf
	v_add_f32_dpp v26, v26, v26 quad_perm:[1,0,3,2] row_mask:0xf bank_mask:0xf
	v_add_f32_dpp v28, v28, v28 quad_perm:[1,0,3,2] row_mask:0xf bank_mask:0xf
	v_pk_fma_f32 v[34:35], v[130:131], v[10:11], v[34:35]
	v_pk_fma_f32 v[42:43], v[130:131], v[18:19], v[42:43]
	v_add_f32_dpp v22, v22, v22 quad_perm:[2,3,0,1] row_mask:0xf bank_mask:0xf
	v_add_f32_dpp v24, v24, v24 quad_perm:[2,3,0,1] row_mask:0xf bank_mask:0xf
	v_add_f32_dpp v26, v26, v26 quad_perm:[2,3,0,1] row_mask:0xf bank_mask:0xf
	v_add_f32_dpp v28, v28, v28 quad_perm:[2,3,0,1] row_mask:0xf bank_mask:0xf
	v_pk_fma_f32 v[36:37], v[132:133], v[12:13], v[36:37]
	v_pk_fma_f32 v[44:45], v[132:133], v[20:21], v[44:45]
	v_add_f32_dpp v22, v22, v22 row_half_mirror row_mask:0xf bank_mask:0xf
	v_add_f32_dpp v24, v24, v24 row_half_mirror row_mask:0xf bank_mask:0xf
	v_add_f32_dpp v26, v26, v26 row_half_mirror row_mask:0xf bank_mask:0xf
	v_add_f32_dpp v28, v28, v28 row_half_mirror row_mask:0xf bank_mask:0xf
	v_pk_fma_f32 v[6:7], v[102:103], v[22:23], v[30:31] op_sel_hi:[1,0,1] neg_lo:[0,1,0] neg_hi:[0,1,0]
	v_pk_fma_f32 v[14:15], v[102:103], v[24:25], v[38:39] op_sel_hi:[1,0,1] neg_lo:[0,1,0] neg_hi:[0,1,0]
	v_pk_fma_f32 v[8:9], v[104:105], v[22:23], v[32:33] op_sel_hi:[1,0,1] neg_lo:[0,1,0] neg_hi:[0,1,0]
	v_pk_fma_f32 v[16:17], v[104:105], v[24:25], v[40:41] op_sel_hi:[1,0,1] neg_lo:[0,1,0] neg_hi:[0,1,0]
	v_cvt_pk_f16_f32 v46, v26, v28
	v_pk_mul_f32 v[26:27], v[6:7], v[118:119]
	v_pk_mul_f32 v[28:29], v[14:15], v[118:119]
	v_pk_fma_f32 v[10:11], v[106:107], v[22:23], v[34:35] op_sel_hi:[1,0,1] neg_lo:[0,1,0] neg_hi:[0,1,0]
	v_pk_fma_f32 v[18:19], v[106:107], v[24:25], v[42:43] op_sel_hi:[1,0,1] neg_lo:[0,1,0] neg_hi:[0,1,0]
	v_pk_fma_f32 v[26:27], v[8:9], v[120:121], v[26:27]
	v_pk_fma_f32 v[28:29], v[16:17], v[120:121], v[28:29]
	v_pk_fma_f32 v[12:13], v[108:109], v[22:23], v[36:37] op_sel_hi:[1,0,1] neg_lo:[0,1,0] neg_hi:[0,1,0]
	v_pk_fma_f32 v[20:21], v[108:109], v[24:25], v[44:45] op_sel_hi:[1,0,1] neg_lo:[0,1,0] neg_hi:[0,1,0]
	v_pk_fma_f32 v[26:27], v[10:11], v[122:123], v[26:27]
	v_pk_fma_f32 v[28:29], v[18:19], v[122:123], v[28:29]
	ds_write_b32 v49, v46 offset:1024
	v_pk_fma_f32 v[26:27], v[12:13], v[124:125], v[26:27]
	v_pk_fma_f32 v[28:29], v[20:21], v[124:125], v[28:29]
	s_waitcnt lgkmcnt(1)
	v_pk_mul_f32 v[22:23], v[6:7], v[52:53]
	v_pk_mul_f32 v[24:25], v[14:15], v[52:53]
	ds_read_b128 v[94:97], v47 offset:2816
	v_add_f32_e32 v26, v26, v27
	v_add_f32_e32 v28, v28, v29
	ds_read_b128 v[98:101], v47 offset:2832
	v_pk_mul_f32 v[30:31], v[68:69], v[92:93] op_sel_hi:[1,0]
	v_pk_mul_f32 v[38:39], v[68:69], v[92:93] op_sel:[0,1]
	ds_read_b128 v[110:113], v47 offset:11008
	v_pk_fma_f32 v[22:23], v[8:9], v[54:55], v[22:23]
	v_pk_fma_f32 v[24:25], v[16:17], v[54:55], v[24:25]
	ds_read_b128 v[114:117], v47 offset:11024
	v_pk_mul_f32 v[32:33], v[70:71], v[92:93] op_sel_hi:[1,0]
	v_pk_mul_f32 v[40:41], v[70:71], v[92:93] op_sel:[0,1]
	ds_read_b64 v[134:135], v48 offset:2816
	v_pk_fma_f32 v[22:23], v[10:11], v[56:57], v[22:23]
	v_pk_fma_f32 v[24:25], v[18:19], v[56:57], v[24:25]
	ds_read_b128 v[126:129], v47 offset:19200
	v_pk_mul_f32 v[34:35], v[72:73], v[92:93] op_sel_hi:[1,0]
	v_pk_mul_f32 v[42:43], v[72:73], v[92:93] op_sel:[0,1]
	ds_read_b128 v[130:133], v47 offset:19216
	v_pk_fma_f32 v[22:23], v[12:13], v[58:59], v[22:23]
	v_pk_fma_f32 v[24:25], v[20:21], v[58:59], v[24:25]
	ds_read_b128 v[102:105], v47 offset:6912
	v_pk_mul_f32 v[36:37], v[74:75], v[92:93] op_sel_hi:[1,0]
	v_pk_mul_f32 v[44:45], v[74:75], v[92:93] op_sel:[0,1]
	ds_read_b128 v[106:109], v47 offset:6928
	v_add_f32_e32 v22, v22, v23
	v_add_f32_e32 v24, v24, v25
	ds_read_b128 v[118:121], v47 offset:15104
	v_pk_fma_f32 v[30:31], v[84:85], v[6:7], v[30:31]
	v_pk_fma_f32 v[38:39], v[84:85], v[14:15], v[38:39]
	ds_read_b128 v[122:125], v47 offset:15120
	v_pk_fma_f32 v[32:33], v[86:87], v[8:9], v[32:33]
	v_pk_fma_f32 v[40:41], v[86:87], v[16:17], v[40:41]
	v_add_f32_dpp v22, v22, v22 quad_perm:[1,0,3,2] row_mask:0xf bank_mask:0xf
	v_add_f32_dpp v24, v24, v24 quad_perm:[1,0,3,2] row_mask:0xf bank_mask:0xf
	v_add_f32_dpp v26, v26, v26 quad_perm:[1,0,3,2] row_mask:0xf bank_mask:0xf
	v_add_f32_dpp v28, v28, v28 quad_perm:[1,0,3,2] row_mask:0xf bank_mask:0xf
	v_pk_fma_f32 v[34:35], v[88:89], v[10:11], v[34:35]
	v_pk_fma_f32 v[42:43], v[88:89], v[18:19], v[42:43]
	v_add_f32_dpp v22, v22, v22 quad_perm:[2,3,0,1] row_mask:0xf bank_mask:0xf
	v_add_f32_dpp v24, v24, v24 quad_perm:[2,3,0,1] row_mask:0xf bank_mask:0xf
	v_add_f32_dpp v26, v26, v26 quad_perm:[2,3,0,1] row_mask:0xf bank_mask:0xf
	v_add_f32_dpp v28, v28, v28 quad_perm:[2,3,0,1] row_mask:0xf bank_mask:0xf
	v_pk_fma_f32 v[36:37], v[90:91], v[12:13], v[36:37]
	v_pk_fma_f32 v[44:45], v[90:91], v[20:21], v[44:45]
	v_add_f32_dpp v22, v22, v22 row_half_mirror row_mask:0xf bank_mask:0xf
	v_add_f32_dpp v24, v24, v24 row_half_mirror row_mask:0xf bank_mask:0xf
	v_add_f32_dpp v26, v26, v26 row_half_mirror row_mask:0xf bank_mask:0xf
	v_add_f32_dpp v28, v28, v28 row_half_mirror row_mask:0xf bank_mask:0xf
	v_pk_fma_f32 v[6:7], v[60:61], v[22:23], v[30:31] op_sel_hi:[1,0,1] neg_lo:[0,1,0] neg_hi:[0,1,0]
	v_pk_fma_f32 v[14:15], v[60:61], v[24:25], v[38:39] op_sel_hi:[1,0,1] neg_lo:[0,1,0] neg_hi:[0,1,0]
	v_pk_fma_f32 v[8:9], v[62:63], v[22:23], v[32:33] op_sel_hi:[1,0,1] neg_lo:[0,1,0] neg_hi:[0,1,0]
	v_pk_fma_f32 v[16:17], v[62:63], v[24:25], v[40:41] op_sel_hi:[1,0,1] neg_lo:[0,1,0] neg_hi:[0,1,0]
	v_cvt_pk_f16_f32 v46, v26, v28
	v_pk_mul_f32 v[26:27], v[6:7], v[76:77]
	v_pk_mul_f32 v[28:29], v[14:15], v[76:77]
	v_pk_fma_f32 v[10:11], v[64:65], v[22:23], v[34:35] op_sel_hi:[1,0,1] neg_lo:[0,1,0] neg_hi:[0,1,0]
	v_pk_fma_f32 v[18:19], v[64:65], v[24:25], v[42:43] op_sel_hi:[1,0,1] neg_lo:[0,1,0] neg_hi:[0,1,0]
	v_pk_fma_f32 v[26:27], v[8:9], v[78:79], v[26:27]
	v_pk_fma_f32 v[28:29], v[16:17], v[78:79], v[28:29]
	v_pk_fma_f32 v[12:13], v[66:67], v[22:23], v[36:37] op_sel_hi:[1,0,1] neg_lo:[0,1,0] neg_hi:[0,1,0]
	v_pk_fma_f32 v[20:21], v[66:67], v[24:25], v[44:45] op_sel_hi:[1,0,1] neg_lo:[0,1,0] neg_hi:[0,1,0]
	v_pk_fma_f32 v[26:27], v[10:11], v[80:81], v[26:27]
	v_pk_fma_f32 v[28:29], v[18:19], v[80:81], v[28:29]
	ds_write_b32 v49, v46 offset:1152
	v_pk_fma_f32 v[26:27], v[12:13], v[82:83], v[26:27]
	v_pk_fma_f32 v[28:29], v[20:21], v[82:83], v[28:29]
	s_waitcnt lgkmcnt(1)
	v_pk_mul_f32 v[22:23], v[6:7], v[94:95]
	v_pk_mul_f32 v[24:25], v[14:15], v[94:95]
	ds_read_b128 v[52:55], v47 offset:3072
	v_add_f32_e32 v26, v26, v27
	v_add_f32_e32 v28, v28, v29
	ds_read_b128 v[56:59], v47 offset:3088
	v_pk_mul_f32 v[30:31], v[110:111], v[134:135] op_sel_hi:[1,0]
	v_pk_mul_f32 v[38:39], v[110:111], v[134:135] op_sel:[0,1]
	ds_read_b128 v[68:71], v47 offset:11264
	v_pk_fma_f32 v[22:23], v[8:9], v[96:97], v[22:23]
	v_pk_fma_f32 v[24:25], v[16:17], v[96:97], v[24:25]
	ds_read_b128 v[72:75], v47 offset:11280
	v_pk_mul_f32 v[32:33], v[112:113], v[134:135] op_sel_hi:[1,0]
	v_pk_mul_f32 v[40:41], v[112:113], v[134:135] op_sel:[0,1]
	ds_read_b64 v[92:93], v48 offset:3072
	v_pk_fma_f32 v[22:23], v[10:11], v[98:99], v[22:23]
	v_pk_fma_f32 v[24:25], v[18:19], v[98:99], v[24:25]
	ds_read_b128 v[84:87], v47 offset:19456
	v_pk_mul_f32 v[34:35], v[114:115], v[134:135] op_sel_hi:[1,0]
	v_pk_mul_f32 v[42:43], v[114:115], v[134:135] op_sel:[0,1]
	ds_read_b128 v[88:91], v47 offset:19472
	v_pk_fma_f32 v[22:23], v[12:13], v[100:101], v[22:23]
	v_pk_fma_f32 v[24:25], v[20:21], v[100:101], v[24:25]
	ds_read_b128 v[60:63], v47 offset:7168
	v_pk_mul_f32 v[36:37], v[116:117], v[134:135] op_sel_hi:[1,0]
	v_pk_mul_f32 v[44:45], v[116:117], v[134:135] op_sel:[0,1]
	ds_read_b128 v[64:67], v47 offset:7184
	v_add_f32_e32 v22, v22, v23
	v_add_f32_e32 v24, v24, v25
	ds_read_b128 v[76:79], v47 offset:15360
	v_pk_fma_f32 v[30:31], v[126:127], v[6:7], v[30:31]
	v_pk_fma_f32 v[38:39], v[126:127], v[14:15], v[38:39]
	ds_read_b128 v[80:83], v47 offset:15376
	v_pk_fma_f32 v[32:33], v[128:129], v[8:9], v[32:33]
	v_pk_fma_f32 v[40:41], v[128:129], v[16:17], v[40:41]
	v_add_f32_dpp v22, v22, v22 quad_perm:[1,0,3,2] row_mask:0xf bank_mask:0xf
	v_add_f32_dpp v24, v24, v24 quad_perm:[1,0,3,2] row_mask:0xf bank_mask:0xf
	v_add_f32_dpp v26, v26, v26 quad_perm:[1,0,3,2] row_mask:0xf bank_mask:0xf
	v_add_f32_dpp v28, v28, v28 quad_perm:[1,0,3,2] row_mask:0xf bank_mask:0xf
	v_pk_fma_f32 v[34:35], v[130:131], v[10:11], v[34:35]
	v_pk_fma_f32 v[42:43], v[130:131], v[18:19], v[42:43]
	v_add_f32_dpp v22, v22, v22 quad_perm:[2,3,0,1] row_mask:0xf bank_mask:0xf
	v_add_f32_dpp v24, v24, v24 quad_perm:[2,3,0,1] row_mask:0xf bank_mask:0xf
	v_add_f32_dpp v26, v26, v26 quad_perm:[2,3,0,1] row_mask:0xf bank_mask:0xf
	v_add_f32_dpp v28, v28, v28 quad_perm:[2,3,0,1] row_mask:0xf bank_mask:0xf
	v_pk_fma_f32 v[36:37], v[132:133], v[12:13], v[36:37]
	v_pk_fma_f32 v[44:45], v[132:133], v[20:21], v[44:45]
	v_add_f32_dpp v22, v22, v22 row_half_mirror row_mask:0xf bank_mask:0xf
	v_add_f32_dpp v24, v24, v24 row_half_mirror row_mask:0xf bank_mask:0xf
	v_add_f32_dpp v26, v26, v26 row_half_mirror row_mask:0xf bank_mask:0xf
	v_add_f32_dpp v28, v28, v28 row_half_mirror row_mask:0xf bank_mask:0xf
	v_pk_fma_f32 v[6:7], v[102:103], v[22:23], v[30:31] op_sel_hi:[1,0,1] neg_lo:[0,1,0] neg_hi:[0,1,0]
	v_pk_fma_f32 v[14:15], v[102:103], v[24:25], v[38:39] op_sel_hi:[1,0,1] neg_lo:[0,1,0] neg_hi:[0,1,0]
	v_pk_fma_f32 v[8:9], v[104:105], v[22:23], v[32:33] op_sel_hi:[1,0,1] neg_lo:[0,1,0] neg_hi:[0,1,0]
	v_pk_fma_f32 v[16:17], v[104:105], v[24:25], v[40:41] op_sel_hi:[1,0,1] neg_lo:[0,1,0] neg_hi:[0,1,0]
	v_cvt_pk_f16_f32 v46, v26, v28
	v_pk_mul_f32 v[26:27], v[6:7], v[118:119]
	v_pk_mul_f32 v[28:29], v[14:15], v[118:119]
	v_pk_fma_f32 v[10:11], v[106:107], v[22:23], v[34:35] op_sel_hi:[1,0,1] neg_lo:[0,1,0] neg_hi:[0,1,0]
	v_pk_fma_f32 v[18:19], v[106:107], v[24:25], v[42:43] op_sel_hi:[1,0,1] neg_lo:[0,1,0] neg_hi:[0,1,0]
	v_pk_fma_f32 v[26:27], v[8:9], v[120:121], v[26:27]
	v_pk_fma_f32 v[28:29], v[16:17], v[120:121], v[28:29]
	v_pk_fma_f32 v[12:13], v[108:109], v[22:23], v[36:37] op_sel_hi:[1,0,1] neg_lo:[0,1,0] neg_hi:[0,1,0]
	v_pk_fma_f32 v[20:21], v[108:109], v[24:25], v[44:45] op_sel_hi:[1,0,1] neg_lo:[0,1,0] neg_hi:[0,1,0]
	v_pk_fma_f32 v[26:27], v[10:11], v[122:123], v[26:27]
	v_pk_fma_f32 v[28:29], v[18:19], v[122:123], v[28:29]
	ds_write_b32 v49, v46 offset:1280
	v_pk_fma_f32 v[26:27], v[12:13], v[124:125], v[26:27]
	v_pk_fma_f32 v[28:29], v[20:21], v[124:125], v[28:29]
	s_waitcnt lgkmcnt(1)
	v_pk_mul_f32 v[22:23], v[6:7], v[52:53]
	v_pk_mul_f32 v[24:25], v[14:15], v[52:53]
	ds_read_b128 v[94:97], v47 offset:3328
	v_add_f32_e32 v26, v26, v27
	v_add_f32_e32 v28, v28, v29
	ds_read_b128 v[98:101], v47 offset:3344
	v_pk_mul_f32 v[30:31], v[68:69], v[92:93] op_sel_hi:[1,0]
	v_pk_mul_f32 v[38:39], v[68:69], v[92:93] op_sel:[0,1]
	ds_read_b128 v[110:113], v47 offset:11520
	v_pk_fma_f32 v[22:23], v[8:9], v[54:55], v[22:23]
	v_pk_fma_f32 v[24:25], v[16:17], v[54:55], v[24:25]
	ds_read_b128 v[114:117], v47 offset:11536
	v_pk_mul_f32 v[32:33], v[70:71], v[92:93] op_sel_hi:[1,0]
	v_pk_mul_f32 v[40:41], v[70:71], v[92:93] op_sel:[0,1]
	ds_read_b64 v[134:135], v48 offset:3328
	v_pk_fma_f32 v[22:23], v[10:11], v[56:57], v[22:23]
	v_pk_fma_f32 v[24:25], v[18:19], v[56:57], v[24:25]
	ds_read_b128 v[126:129], v47 offset:19712
	v_pk_mul_f32 v[34:35], v[72:73], v[92:93] op_sel_hi:[1,0]
	v_pk_mul_f32 v[42:43], v[72:73], v[92:93] op_sel:[0,1]
	ds_read_b128 v[130:133], v47 offset:19728
	v_pk_fma_f32 v[22:23], v[12:13], v[58:59], v[22:23]
	v_pk_fma_f32 v[24:25], v[20:21], v[58:59], v[24:25]
	ds_read_b128 v[102:105], v47 offset:7424
	v_pk_mul_f32 v[36:37], v[74:75], v[92:93] op_sel_hi:[1,0]
	v_pk_mul_f32 v[44:45], v[74:75], v[92:93] op_sel:[0,1]
	ds_read_b128 v[106:109], v47 offset:7440
	v_add_f32_e32 v22, v22, v23
	v_add_f32_e32 v24, v24, v25
	ds_read_b128 v[118:121], v47 offset:15616
	v_pk_fma_f32 v[30:31], v[84:85], v[6:7], v[30:31]
	v_pk_fma_f32 v[38:39], v[84:85], v[14:15], v[38:39]
	ds_read_b128 v[122:125], v47 offset:15632
	v_pk_fma_f32 v[32:33], v[86:87], v[8:9], v[32:33]
	v_pk_fma_f32 v[40:41], v[86:87], v[16:17], v[40:41]
	v_add_f32_dpp v22, v22, v22 quad_perm:[1,0,3,2] row_mask:0xf bank_mask:0xf
	v_add_f32_dpp v24, v24, v24 quad_perm:[1,0,3,2] row_mask:0xf bank_mask:0xf
	v_add_f32_dpp v26, v26, v26 quad_perm:[1,0,3,2] row_mask:0xf bank_mask:0xf
	v_add_f32_dpp v28, v28, v28 quad_perm:[1,0,3,2] row_mask:0xf bank_mask:0xf
	v_pk_fma_f32 v[34:35], v[88:89], v[10:11], v[34:35]
	v_pk_fma_f32 v[42:43], v[88:89], v[18:19], v[42:43]
	v_add_f32_dpp v22, v22, v22 quad_perm:[2,3,0,1] row_mask:0xf bank_mask:0xf
	v_add_f32_dpp v24, v24, v24 quad_perm:[2,3,0,1] row_mask:0xf bank_mask:0xf
	v_add_f32_dpp v26, v26, v26 quad_perm:[2,3,0,1] row_mask:0xf bank_mask:0xf
	v_add_f32_dpp v28, v28, v28 quad_perm:[2,3,0,1] row_mask:0xf bank_mask:0xf
	v_pk_fma_f32 v[36:37], v[90:91], v[12:13], v[36:37]
	v_pk_fma_f32 v[44:45], v[90:91], v[20:21], v[44:45]
	v_add_f32_dpp v22, v22, v22 row_half_mirror row_mask:0xf bank_mask:0xf
	v_add_f32_dpp v24, v24, v24 row_half_mirror row_mask:0xf bank_mask:0xf
	v_add_f32_dpp v26, v26, v26 row_half_mirror row_mask:0xf bank_mask:0xf
	v_add_f32_dpp v28, v28, v28 row_half_mirror row_mask:0xf bank_mask:0xf
	v_pk_fma_f32 v[6:7], v[60:61], v[22:23], v[30:31] op_sel_hi:[1,0,1] neg_lo:[0,1,0] neg_hi:[0,1,0]
	v_pk_fma_f32 v[14:15], v[60:61], v[24:25], v[38:39] op_sel_hi:[1,0,1] neg_lo:[0,1,0] neg_hi:[0,1,0]
	v_pk_fma_f32 v[8:9], v[62:63], v[22:23], v[32:33] op_sel_hi:[1,0,1] neg_lo:[0,1,0] neg_hi:[0,1,0]
	v_pk_fma_f32 v[16:17], v[62:63], v[24:25], v[40:41] op_sel_hi:[1,0,1] neg_lo:[0,1,0] neg_hi:[0,1,0]
	v_cvt_pk_f16_f32 v46, v26, v28
	v_pk_mul_f32 v[26:27], v[6:7], v[76:77]
	v_pk_mul_f32 v[28:29], v[14:15], v[76:77]
	v_pk_fma_f32 v[10:11], v[64:65], v[22:23], v[34:35] op_sel_hi:[1,0,1] neg_lo:[0,1,0] neg_hi:[0,1,0]
	v_pk_fma_f32 v[18:19], v[64:65], v[24:25], v[42:43] op_sel_hi:[1,0,1] neg_lo:[0,1,0] neg_hi:[0,1,0]
	v_pk_fma_f32 v[26:27], v[8:9], v[78:79], v[26:27]
	v_pk_fma_f32 v[28:29], v[16:17], v[78:79], v[28:29]
	v_pk_fma_f32 v[12:13], v[66:67], v[22:23], v[36:37] op_sel_hi:[1,0,1] neg_lo:[0,1,0] neg_hi:[0,1,0]
	v_pk_fma_f32 v[20:21], v[66:67], v[24:25], v[44:45] op_sel_hi:[1,0,1] neg_lo:[0,1,0] neg_hi:[0,1,0]
	v_pk_fma_f32 v[26:27], v[10:11], v[80:81], v[26:27]
	v_pk_fma_f32 v[28:29], v[18:19], v[80:81], v[28:29]
	ds_write_b32 v49, v46 offset:1408
	v_pk_fma_f32 v[26:27], v[12:13], v[82:83], v[26:27]
	v_pk_fma_f32 v[28:29], v[20:21], v[82:83], v[28:29]
	s_waitcnt lgkmcnt(1)
	v_pk_mul_f32 v[22:23], v[6:7], v[94:95]
	v_pk_mul_f32 v[24:25], v[14:15], v[94:95]
	ds_read_b128 v[52:55], v47 offset:3584
	v_add_f32_e32 v26, v26, v27
	v_add_f32_e32 v28, v28, v29
	ds_read_b128 v[56:59], v47 offset:3600
	v_pk_mul_f32 v[30:31], v[110:111], v[134:135] op_sel_hi:[1,0]
	v_pk_mul_f32 v[38:39], v[110:111], v[134:135] op_sel:[0,1]
	ds_read_b128 v[68:71], v47 offset:11776
	v_pk_fma_f32 v[22:23], v[8:9], v[96:97], v[22:23]
	v_pk_fma_f32 v[24:25], v[16:17], v[96:97], v[24:25]
	ds_read_b128 v[72:75], v47 offset:11792
	v_pk_mul_f32 v[32:33], v[112:113], v[134:135] op_sel_hi:[1,0]
	v_pk_mul_f32 v[40:41], v[112:113], v[134:135] op_sel:[0,1]
	ds_read_b64 v[92:93], v48 offset:3584
	v_pk_fma_f32 v[22:23], v[10:11], v[98:99], v[22:23]
	v_pk_fma_f32 v[24:25], v[18:19], v[98:99], v[24:25]
	ds_read_b128 v[84:87], v47 offset:19968
	v_pk_mul_f32 v[34:35], v[114:115], v[134:135] op_sel_hi:[1,0]
	v_pk_mul_f32 v[42:43], v[114:115], v[134:135] op_sel:[0,1]
	ds_read_b128 v[88:91], v47 offset:19984
	v_pk_fma_f32 v[22:23], v[12:13], v[100:101], v[22:23]
	v_pk_fma_f32 v[24:25], v[20:21], v[100:101], v[24:25]
	ds_read_b128 v[60:63], v47 offset:7680
	v_pk_mul_f32 v[36:37], v[116:117], v[134:135] op_sel_hi:[1,0]
	v_pk_mul_f32 v[44:45], v[116:117], v[134:135] op_sel:[0,1]
	ds_read_b128 v[64:67], v47 offset:7696
	v_add_f32_e32 v22, v22, v23
	v_add_f32_e32 v24, v24, v25
	ds_read_b128 v[76:79], v47 offset:15872
	v_pk_fma_f32 v[30:31], v[126:127], v[6:7], v[30:31]
	v_pk_fma_f32 v[38:39], v[126:127], v[14:15], v[38:39]
	ds_read_b128 v[80:83], v47 offset:15888
	v_pk_fma_f32 v[32:33], v[128:129], v[8:9], v[32:33]
	v_pk_fma_f32 v[40:41], v[128:129], v[16:17], v[40:41]
	v_add_f32_dpp v22, v22, v22 quad_perm:[1,0,3,2] row_mask:0xf bank_mask:0xf
	v_add_f32_dpp v24, v24, v24 quad_perm:[1,0,3,2] row_mask:0xf bank_mask:0xf
	v_add_f32_dpp v26, v26, v26 quad_perm:[1,0,3,2] row_mask:0xf bank_mask:0xf
	v_add_f32_dpp v28, v28, v28 quad_perm:[1,0,3,2] row_mask:0xf bank_mask:0xf
	v_pk_fma_f32 v[34:35], v[130:131], v[10:11], v[34:35]
	v_pk_fma_f32 v[42:43], v[130:131], v[18:19], v[42:43]
	v_add_f32_dpp v22, v22, v22 quad_perm:[2,3,0,1] row_mask:0xf bank_mask:0xf
	v_add_f32_dpp v24, v24, v24 quad_perm:[2,3,0,1] row_mask:0xf bank_mask:0xf
	v_add_f32_dpp v26, v26, v26 quad_perm:[2,3,0,1] row_mask:0xf bank_mask:0xf
	v_add_f32_dpp v28, v28, v28 quad_perm:[2,3,0,1] row_mask:0xf bank_mask:0xf
	v_pk_fma_f32 v[36:37], v[132:133], v[12:13], v[36:37]
	v_pk_fma_f32 v[44:45], v[132:133], v[20:21], v[44:45]
	v_add_f32_dpp v22, v22, v22 row_half_mirror row_mask:0xf bank_mask:0xf
	v_add_f32_dpp v24, v24, v24 row_half_mirror row_mask:0xf bank_mask:0xf
	v_add_f32_dpp v26, v26, v26 row_half_mirror row_mask:0xf bank_mask:0xf
	v_add_f32_dpp v28, v28, v28 row_half_mirror row_mask:0xf bank_mask:0xf
	v_pk_fma_f32 v[6:7], v[102:103], v[22:23], v[30:31] op_sel_hi:[1,0,1] neg_lo:[0,1,0] neg_hi:[0,1,0]
	v_pk_fma_f32 v[14:15], v[102:103], v[24:25], v[38:39] op_sel_hi:[1,0,1] neg_lo:[0,1,0] neg_hi:[0,1,0]
	v_pk_fma_f32 v[8:9], v[104:105], v[22:23], v[32:33] op_sel_hi:[1,0,1] neg_lo:[0,1,0] neg_hi:[0,1,0]
	v_pk_fma_f32 v[16:17], v[104:105], v[24:25], v[40:41] op_sel_hi:[1,0,1] neg_lo:[0,1,0] neg_hi:[0,1,0]
	v_cvt_pk_f16_f32 v46, v26, v28
	v_pk_mul_f32 v[26:27], v[6:7], v[118:119]
	v_pk_mul_f32 v[28:29], v[14:15], v[118:119]
	v_pk_fma_f32 v[10:11], v[106:107], v[22:23], v[34:35] op_sel_hi:[1,0,1] neg_lo:[0,1,0] neg_hi:[0,1,0]
	v_pk_fma_f32 v[18:19], v[106:107], v[24:25], v[42:43] op_sel_hi:[1,0,1] neg_lo:[0,1,0] neg_hi:[0,1,0]
	v_pk_fma_f32 v[26:27], v[8:9], v[120:121], v[26:27]
	v_pk_fma_f32 v[28:29], v[16:17], v[120:121], v[28:29]
	v_pk_fma_f32 v[12:13], v[108:109], v[22:23], v[36:37] op_sel_hi:[1,0,1] neg_lo:[0,1,0] neg_hi:[0,1,0]
	v_pk_fma_f32 v[20:21], v[108:109], v[24:25], v[44:45] op_sel_hi:[1,0,1] neg_lo:[0,1,0] neg_hi:[0,1,0]
	v_pk_fma_f32 v[26:27], v[10:11], v[122:123], v[26:27]
	v_pk_fma_f32 v[28:29], v[18:19], v[122:123], v[28:29]
	ds_write_b32 v49, v46 offset:1536
	v_pk_fma_f32 v[26:27], v[12:13], v[124:125], v[26:27]
	v_pk_fma_f32 v[28:29], v[20:21], v[124:125], v[28:29]
	s_waitcnt lgkmcnt(1)
	v_pk_mul_f32 v[22:23], v[6:7], v[52:53]
	v_pk_mul_f32 v[24:25], v[14:15], v[52:53]
	ds_read_b128 v[94:97], v47 offset:3840
	v_add_f32_e32 v26, v26, v27
	v_add_f32_e32 v28, v28, v29
	ds_read_b128 v[98:101], v47 offset:3856
	v_pk_mul_f32 v[30:31], v[68:69], v[92:93] op_sel_hi:[1,0]
	v_pk_mul_f32 v[38:39], v[68:69], v[92:93] op_sel:[0,1]
	ds_read_b128 v[110:113], v47 offset:12032
	v_pk_fma_f32 v[22:23], v[8:9], v[54:55], v[22:23]
	v_pk_fma_f32 v[24:25], v[16:17], v[54:55], v[24:25]
	ds_read_b128 v[114:117], v47 offset:12048
	v_pk_mul_f32 v[32:33], v[70:71], v[92:93] op_sel_hi:[1,0]
	v_pk_mul_f32 v[40:41], v[70:71], v[92:93] op_sel:[0,1]
	ds_read_b64 v[134:135], v48 offset:3840
	v_pk_fma_f32 v[22:23], v[10:11], v[56:57], v[22:23]
	v_pk_fma_f32 v[24:25], v[18:19], v[56:57], v[24:25]
	ds_read_b128 v[126:129], v47 offset:20224
	v_pk_mul_f32 v[34:35], v[72:73], v[92:93] op_sel_hi:[1,0]
	v_pk_mul_f32 v[42:43], v[72:73], v[92:93] op_sel:[0,1]
	ds_read_b128 v[130:133], v47 offset:20240
	v_pk_fma_f32 v[22:23], v[12:13], v[58:59], v[22:23]
	v_pk_fma_f32 v[24:25], v[20:21], v[58:59], v[24:25]
	ds_read_b128 v[102:105], v47 offset:7936
	v_pk_mul_f32 v[36:37], v[74:75], v[92:93] op_sel_hi:[1,0]
	v_pk_mul_f32 v[44:45], v[74:75], v[92:93] op_sel:[0,1]
	ds_read_b128 v[106:109], v47 offset:7952
	v_add_f32_e32 v22, v22, v23
	v_add_f32_e32 v24, v24, v25
	ds_read_b128 v[118:121], v47 offset:16128
	v_pk_fma_f32 v[30:31], v[84:85], v[6:7], v[30:31]
	v_pk_fma_f32 v[38:39], v[84:85], v[14:15], v[38:39]
	ds_read_b128 v[122:125], v47 offset:16144
	v_pk_fma_f32 v[32:33], v[86:87], v[8:9], v[32:33]
	v_pk_fma_f32 v[40:41], v[86:87], v[16:17], v[40:41]
	v_add_f32_dpp v22, v22, v22 quad_perm:[1,0,3,2] row_mask:0xf bank_mask:0xf
	v_add_f32_dpp v24, v24, v24 quad_perm:[1,0,3,2] row_mask:0xf bank_mask:0xf
	v_add_f32_dpp v26, v26, v26 quad_perm:[1,0,3,2] row_mask:0xf bank_mask:0xf
	v_add_f32_dpp v28, v28, v28 quad_perm:[1,0,3,2] row_mask:0xf bank_mask:0xf
	v_pk_fma_f32 v[34:35], v[88:89], v[10:11], v[34:35]
	v_pk_fma_f32 v[42:43], v[88:89], v[18:19], v[42:43]
	v_add_f32_dpp v22, v22, v22 quad_perm:[2,3,0,1] row_mask:0xf bank_mask:0xf
	v_add_f32_dpp v24, v24, v24 quad_perm:[2,3,0,1] row_mask:0xf bank_mask:0xf
	v_add_f32_dpp v26, v26, v26 quad_perm:[2,3,0,1] row_mask:0xf bank_mask:0xf
	v_add_f32_dpp v28, v28, v28 quad_perm:[2,3,0,1] row_mask:0xf bank_mask:0xf
	v_pk_fma_f32 v[36:37], v[90:91], v[12:13], v[36:37]
	v_pk_fma_f32 v[44:45], v[90:91], v[20:21], v[44:45]
	v_add_f32_dpp v22, v22, v22 row_half_mirror row_mask:0xf bank_mask:0xf
	v_add_f32_dpp v24, v24, v24 row_half_mirror row_mask:0xf bank_mask:0xf
	v_add_f32_dpp v26, v26, v26 row_half_mirror row_mask:0xf bank_mask:0xf
	v_add_f32_dpp v28, v28, v28 row_half_mirror row_mask:0xf bank_mask:0xf
	v_pk_fma_f32 v[6:7], v[60:61], v[22:23], v[30:31] op_sel_hi:[1,0,1] neg_lo:[0,1,0] neg_hi:[0,1,0]
	v_pk_fma_f32 v[14:15], v[60:61], v[24:25], v[38:39] op_sel_hi:[1,0,1] neg_lo:[0,1,0] neg_hi:[0,1,0]
	v_pk_fma_f32 v[8:9], v[62:63], v[22:23], v[32:33] op_sel_hi:[1,0,1] neg_lo:[0,1,0] neg_hi:[0,1,0]
	v_pk_fma_f32 v[16:17], v[62:63], v[24:25], v[40:41] op_sel_hi:[1,0,1] neg_lo:[0,1,0] neg_hi:[0,1,0]
	v_cvt_pk_f16_f32 v46, v26, v28
	v_pk_mul_f32 v[26:27], v[6:7], v[76:77]
	v_pk_mul_f32 v[28:29], v[14:15], v[76:77]
	v_pk_fma_f32 v[10:11], v[64:65], v[22:23], v[34:35] op_sel_hi:[1,0,1] neg_lo:[0,1,0] neg_hi:[0,1,0]
	v_pk_fma_f32 v[18:19], v[64:65], v[24:25], v[42:43] op_sel_hi:[1,0,1] neg_lo:[0,1,0] neg_hi:[0,1,0]
	v_pk_fma_f32 v[26:27], v[8:9], v[78:79], v[26:27]
	v_pk_fma_f32 v[28:29], v[16:17], v[78:79], v[28:29]
	v_pk_fma_f32 v[12:13], v[66:67], v[22:23], v[36:37] op_sel_hi:[1,0,1] neg_lo:[0,1,0] neg_hi:[0,1,0]
	v_pk_fma_f32 v[20:21], v[66:67], v[24:25], v[44:45] op_sel_hi:[1,0,1] neg_lo:[0,1,0] neg_hi:[0,1,0]
	v_pk_fma_f32 v[26:27], v[10:11], v[80:81], v[26:27]
	v_pk_fma_f32 v[28:29], v[18:19], v[80:81], v[28:29]
	ds_write_b32 v49, v46 offset:1664
	v_pk_fma_f32 v[26:27], v[12:13], v[82:83], v[26:27]
	v_pk_fma_f32 v[28:29], v[20:21], v[82:83], v[28:29]
	s_waitcnt lgkmcnt(1)
	v_pk_mul_f32 v[22:23], v[6:7], v[94:95]
	v_pk_mul_f32 v[24:25], v[14:15], v[94:95]
	v_add_f32_e32 v26, v26, v27
	v_add_f32_e32 v28, v28, v29
	v_pk_mul_f32 v[30:31], v[110:111], v[134:135] op_sel_hi:[1,0]
	v_pk_mul_f32 v[38:39], v[110:111], v[134:135] op_sel:[0,1]
	v_pk_fma_f32 v[22:23], v[8:9], v[96:97], v[22:23]
	v_pk_fma_f32 v[24:25], v[16:17], v[96:97], v[24:25]
	v_pk_mul_f32 v[32:33], v[112:113], v[134:135] op_sel_hi:[1,0]
	v_pk_mul_f32 v[40:41], v[112:113], v[134:135] op_sel:[0,1]
	v_pk_fma_f32 v[22:23], v[10:11], v[98:99], v[22:23]
	v_pk_fma_f32 v[24:25], v[18:19], v[98:99], v[24:25]
	v_pk_mul_f32 v[34:35], v[114:115], v[134:135] op_sel_hi:[1,0]
	v_pk_mul_f32 v[42:43], v[114:115], v[134:135] op_sel:[0,1]
	v_pk_fma_f32 v[22:23], v[12:13], v[100:101], v[22:23]
	v_pk_fma_f32 v[24:25], v[20:21], v[100:101], v[24:25]
	v_pk_mul_f32 v[36:37], v[116:117], v[134:135] op_sel_hi:[1,0]
	v_pk_mul_f32 v[44:45], v[116:117], v[134:135] op_sel:[0,1]
	v_add_f32_e32 v22, v22, v23
	v_add_f32_e32 v24, v24, v25
	v_pk_fma_f32 v[30:31], v[126:127], v[6:7], v[30:31]
	v_pk_fma_f32 v[38:39], v[126:127], v[14:15], v[38:39]
	v_pk_fma_f32 v[32:33], v[128:129], v[8:9], v[32:33]
	v_pk_fma_f32 v[40:41], v[128:129], v[16:17], v[40:41]
	v_add_f32_dpp v22, v22, v22 quad_perm:[1,0,3,2] row_mask:0xf bank_mask:0xf
	v_add_f32_dpp v24, v24, v24 quad_perm:[1,0,3,2] row_mask:0xf bank_mask:0xf
	v_add_f32_dpp v26, v26, v26 quad_perm:[1,0,3,2] row_mask:0xf bank_mask:0xf
	v_add_f32_dpp v28, v28, v28 quad_perm:[1,0,3,2] row_mask:0xf bank_mask:0xf
	v_pk_fma_f32 v[34:35], v[130:131], v[10:11], v[34:35]
	v_pk_fma_f32 v[42:43], v[130:131], v[18:19], v[42:43]
	v_add_f32_dpp v22, v22, v22 quad_perm:[2,3,0,1] row_mask:0xf bank_mask:0xf
	v_add_f32_dpp v24, v24, v24 quad_perm:[2,3,0,1] row_mask:0xf bank_mask:0xf
	v_add_f32_dpp v26, v26, v26 quad_perm:[2,3,0,1] row_mask:0xf bank_mask:0xf
	v_add_f32_dpp v28, v28, v28 quad_perm:[2,3,0,1] row_mask:0xf bank_mask:0xf
	v_pk_fma_f32 v[36:37], v[132:133], v[12:13], v[36:37]
	v_pk_fma_f32 v[44:45], v[132:133], v[20:21], v[44:45]
	v_add_f32_dpp v22, v22, v22 row_half_mirror row_mask:0xf bank_mask:0xf
	v_add_f32_dpp v24, v24, v24 row_half_mirror row_mask:0xf bank_mask:0xf
	v_add_f32_dpp v26, v26, v26 row_half_mirror row_mask:0xf bank_mask:0xf
	v_add_f32_dpp v28, v28, v28 row_half_mirror row_mask:0xf bank_mask:0xf
	v_pk_fma_f32 v[6:7], v[102:103], v[22:23], v[30:31] op_sel_hi:[1,0,1] neg_lo:[0,1,0] neg_hi:[0,1,0]
	v_pk_fma_f32 v[14:15], v[102:103], v[24:25], v[38:39] op_sel_hi:[1,0,1] neg_lo:[0,1,0] neg_hi:[0,1,0]
	v_pk_fma_f32 v[8:9], v[104:105], v[22:23], v[32:33] op_sel_hi:[1,0,1] neg_lo:[0,1,0] neg_hi:[0,1,0]
	v_pk_fma_f32 v[16:17], v[104:105], v[24:25], v[40:41] op_sel_hi:[1,0,1] neg_lo:[0,1,0] neg_hi:[0,1,0]
	v_cvt_pk_f16_f32 v46, v26, v28
	v_pk_mul_f32 v[26:27], v[6:7], v[118:119]
	v_pk_mul_f32 v[28:29], v[14:15], v[118:119]
	v_pk_fma_f32 v[10:11], v[106:107], v[22:23], v[34:35] op_sel_hi:[1,0,1] neg_lo:[0,1,0] neg_hi:[0,1,0]
	v_pk_fma_f32 v[18:19], v[106:107], v[24:25], v[42:43] op_sel_hi:[1,0,1] neg_lo:[0,1,0] neg_hi:[0,1,0]
	v_pk_fma_f32 v[26:27], v[8:9], v[120:121], v[26:27]
	v_pk_fma_f32 v[28:29], v[16:17], v[120:121], v[28:29]
	v_pk_fma_f32 v[12:13], v[108:109], v[22:23], v[36:37] op_sel_hi:[1,0,1] neg_lo:[0,1,0] neg_hi:[0,1,0]
	v_pk_fma_f32 v[20:21], v[108:109], v[24:25], v[44:45] op_sel_hi:[1,0,1] neg_lo:[0,1,0] neg_hi:[0,1,0]
	v_pk_fma_f32 v[26:27], v[10:11], v[122:123], v[26:27]
	v_pk_fma_f32 v[28:29], v[18:19], v[122:123], v[28:29]
	ds_write_b32 v49, v46 offset:1792
	v_pk_fma_f32 v[26:27], v[12:13], v[124:125], v[26:27]
	v_pk_fma_f32 v[28:29], v[20:21], v[124:125], v[28:29]
	v_add_f32_e32 v26, v26, v27
	v_add_f32_e32 v28, v28, v29
	s_nop 0
	v_add_f32_dpp v26, v26, v26 quad_perm:[1,0,3,2] row_mask:0xf bank_mask:0xf
	v_add_f32_dpp v28, v28, v28 quad_perm:[1,0,3,2] row_mask:0xf bank_mask:0xf
	s_nop 0
	v_add_f32_dpp v26, v26, v26 quad_perm:[2,3,0,1] row_mask:0xf bank_mask:0xf
	v_add_f32_dpp v28, v28, v28 quad_perm:[2,3,0,1] row_mask:0xf bank_mask:0xf
	s_nop 0
	v_add_f32_dpp v26, v26, v26 row_half_mirror row_mask:0xf bank_mask:0xf
	v_add_f32_dpp v28, v28, v28 row_half_mirror row_mask:0xf bank_mask:0xf
	s_nop 0
	v_cvt_pk_f16_f32 v46, v26, v28
	s_nop 0
	ds_write_b32 v49, v46 offset:1920
	s_cmp_eq_u32 s38, 0
	s_cbranch_scc1 .Lsc_nofin
	s_cmp_lg_u32 s53, 15
	s_cbranch_scc1 .Lsc_nofin
	s_lshr_b32 s55, s33, 4
	s_lshl_b32 s55, s55, 1
	s_lshr_b32 s56, s43, 4
	s_add_u32 s55, s55, s56
	s_lshl_b32 s55, s55, 2
	s_lshr_b32 s56, s42, 1
	s_add_u32 s55, s55, s56
	s_cmp_eq_u32 s38, 0
	s_cselect_b32 s54, s42, s55
	s_lshl_b32 s54, s54, 1
	s_add_u32 s54, s54, s44
	s_lshl_b32 s54, s54, 1
	s_add_u32 s54, s54, s50
	s_lshl_b32 s54, s54, 4
	s_add_u32 s54, s54, s46
	s_lshl_b32 s54, s54, 14
	s_add_u32 s54, s54, 0xc000000
	s_add_u32 s30, s34, s54
	s_addc_u32 s31, s35, 0
	global_store_dwordx4 v3, v[6:9], s[30:31]
	global_store_dwordx4 v3, v[10:13], s[30:31] offset:16
	global_store_dwordx4 v3, v[14:17], s[30:31] offset:256
	global_store_dwordx4 v3, v[18:21], s[30:31] offset:272
